# gemm_stream K loops regrouped: 2 super-phases of 32 MFMAs per K tile (4 barriers instead of 8), LDS reads drained and stage loads counted before each load-interval barrier
# speedup vs baseline: 1.0401x; 1.0271x over previous
.LBB0_32:
	s_add_i32 s11, s10, 2
	ds_read_b128 v[132:135], v159
	ds_read_b128 v[136:139], v160
	ds_read_b128 v[180:183], v161
	ds_read_b128 v[184:187], v162
	s_cmpk_lt_u32 s10, 0x56
	s_cselect_b32 s12, s8, s5
	s_cselect_b32 s13, s7, s6
	s_cselect_b32 s14, s9, 0
	s_mulk_i32 s13, 0x1600
	s_mulk_i32 s12, 0x1600
	s_or_b32 s15, s14, 64
	s_add_i32 s17, s12, s14
	s_add_i32 s18, s13, 0xb0000
	s_add_i32 s16, s13, s14
	s_add_i32 s13, s15, s13
	s_add_i32 s12, s15, s12
	s_lshl_b32 s17, s17, 1
	s_add_i32 s14, s18, s14
	s_add_i32 s18, s18, s15
	s_addk_i32 s9, 0x80
	s_lshl_b32 s16, s16, 1
	s_lshl_b32 s19, s13, 1
	s_lshl_b32 s13, s12, 1
	s_lshl_b32 s14, s14, 1
	s_add_i32 s15, s17, 0x160000
	s_lshl_b32 s12, s18, 1
	s_cmpk_gt_u32 s10, 0x55
	v_readfirstlane_b32 s10, v163
	v_add_u32_e32 v131, 0xfff50000, v130
	s_mov_b32 m0, s10
	v_readfirstlane_b32 s10, v165
	ds_read_b128 v[188:191], v157
	ds_read_b128 v[192:195], v157 offset:1024
	ds_read_b128 v[196:199], v157 offset:2048
	ds_read_b128 v[200:203], v157 offset:3072
	ds_read_b128 v[204:207], v157 offset:4096
	ds_read_b128 v[208:211], v157 offset:5120
	ds_read_b128 v[212:215], v157 offset:6144
	ds_read_b128 v[216:219], v157 offset:7168
	global_load_lds_dwordx4 v131, s[76:77]
	s_mov_b32 m0, s10
	s_nop 0
	global_load_lds_dwordx4 v130, s[76:77]
	ds_read_b128 v[220:223], v166
	ds_read_b128 v[242:245], v167
	ds_read_b128 v[246:249], v168
	ds_read_b128 v[250:253], v169
	s_waitcnt vmcnt(8)
	s_waitcnt lgkmcnt(0)
	s_barrier
	s_setprio 1
	v_mfma_f32_16x16x32_bf16 v[126:129], v[132:135], v[188:191], v[126:129]
	v_mfma_f32_16x16x32_bf16 v[122:125], v[180:183], v[188:191], v[122:125]
	v_mfma_f32_16x16x32_bf16 v[118:121], v[132:135], v[196:199], v[118:121]
	v_mfma_f32_16x16x32_bf16 v[114:117], v[180:183], v[196:199], v[114:117]
	v_mfma_f32_16x16x32_bf16 v[110:113], v[132:135], v[204:207], v[110:113]
	v_mfma_f32_16x16x32_bf16 v[106:109], v[180:183], v[204:207], v[106:109]
	v_mfma_f32_16x16x32_bf16 v[102:105], v[132:135], v[212:215], v[102:105]
	v_mfma_f32_16x16x32_bf16 v[98:101], v[180:183], v[212:215], v[98:101]
	v_mfma_f32_16x16x32_bf16 v[126:129], v[136:139], v[192:195], v[126:129]
	v_mfma_f32_16x16x32_bf16 v[122:125], v[184:187], v[192:195], v[122:125]
	v_mfma_f32_16x16x32_bf16 v[118:121], v[136:139], v[200:203], v[118:121]
	v_mfma_f32_16x16x32_bf16 v[114:117], v[184:187], v[200:203], v[114:117]
	v_mfma_f32_16x16x32_bf16 v[110:113], v[136:139], v[208:211], v[110:113]
	v_mfma_f32_16x16x32_bf16 v[106:109], v[184:187], v[208:211], v[106:109]
	v_mfma_f32_16x16x32_bf16 v[102:105], v[136:139], v[216:219], v[102:105]
	v_mfma_f32_16x16x32_bf16 v[98:101], v[184:187], v[216:219], v[98:101]
	v_mfma_f32_16x16x32_bf16 v[94:97], v[220:223], v[188:191], v[94:97]
	v_mfma_f32_16x16x32_bf16 v[90:93], v[246:249], v[188:191], v[90:93]
	v_mfma_f32_16x16x32_bf16 v[86:89], v[220:223], v[196:199], v[86:89]
	v_mfma_f32_16x16x32_bf16 v[82:85], v[246:249], v[196:199], v[82:85]
	v_mfma_f32_16x16x32_bf16 v[78:81], v[220:223], v[204:207], v[78:81]
	v_mfma_f32_16x16x32_bf16 v[74:77], v[246:249], v[204:207], v[74:77]
	v_mfma_f32_16x16x32_bf16 v[70:73], v[220:223], v[212:215], v[70:73]
	v_mfma_f32_16x16x32_bf16 v[66:69], v[246:249], v[212:215], v[66:69]
	v_mfma_f32_16x16x32_bf16 v[94:97], v[242:245], v[192:195], v[94:97]
	v_mfma_f32_16x16x32_bf16 v[90:93], v[250:253], v[192:195], v[90:93]
	v_mfma_f32_16x16x32_bf16 v[86:89], v[242:245], v[200:203], v[86:89]
	v_mfma_f32_16x16x32_bf16 v[82:85], v[250:253], v[200:203], v[82:85]
	v_mfma_f32_16x16x32_bf16 v[78:81], v[242:245], v[208:211], v[78:81]
	v_mfma_f32_16x16x32_bf16 v[74:77], v[250:253], v[208:211], v[74:77]
	v_mfma_f32_16x16x32_bf16 v[70:73], v[242:245], v[216:219], v[70:73]
	v_mfma_f32_16x16x32_bf16 v[66:69], v[250:253], v[216:219], v[66:69]
	s_setprio 0
	s_barrier
	v_readfirstlane_b32 s10, v144
	v_add_u32_e32 v131, s16, v142
	s_mov_b32 m0, s10
	v_readfirstlane_b32 s10, v145
	global_load_lds_dwordx4 v131, s[78:79]
	v_add_u32_e32 v131, s16, v143
	s_mov_b32 m0, s10
	s_nop 0
	global_load_lds_dwordx4 v131, s[78:79]
	v_readfirstlane_b32 s10, v0
	v_add_u32_e32 v131, s17, v142
	s_mov_b32 m0, s10
	v_readfirstlane_b32 s10, v146
	ds_read_b128 v[188:191], v157 offset:16384
	ds_read_b128 v[192:195], v157 offset:17408
	ds_read_b128 v[196:199], v157 offset:18432
	ds_read_b128 v[200:203], v157 offset:19456
	ds_read_b128 v[204:207], v157 offset:20480
	ds_read_b128 v[208:211], v157 offset:21504
	ds_read_b128 v[212:215], v157 offset:22528
	ds_read_b128 v[216:219], v157 offset:23552
	global_load_lds_dwordx4 v131, s[76:77]
	v_add_u32_e32 v131, s17, v143
	s_mov_b32 m0, s10
	s_nop 0
	global_load_lds_dwordx4 v131, s[76:77]
	v_readfirstlane_b32 s10, v147
	v_add_u32_e32 v131, s14, v142
	s_mov_b32 m0, s10
	v_readfirstlane_b32 s10, v148
	global_load_lds_dwordx4 v131, s[78:79]
	v_add_u32_e32 v131, s14, v143
	s_mov_b32 m0, s10
	s_nop 0
	global_load_lds_dwordx4 v131, s[78:79]
	s_waitcnt vmcnt(8)
	s_waitcnt lgkmcnt(0)
	s_barrier
	s_setprio 1
	v_mfma_f32_16x16x32_bf16 v[62:65], v[132:135], v[188:191], v[62:65]
	v_mfma_f32_16x16x32_bf16 v[58:61], v[180:183], v[188:191], v[58:61]
	v_mfma_f32_16x16x32_bf16 v[54:57], v[132:135], v[196:199], v[54:57]
	v_mfma_f32_16x16x32_bf16 v[50:53], v[180:183], v[196:199], v[50:53]
	v_mfma_f32_16x16x32_bf16 v[46:49], v[132:135], v[204:207], v[46:49]
	v_mfma_f32_16x16x32_bf16 v[42:45], v[180:183], v[204:207], v[42:45]
	v_mfma_f32_16x16x32_bf16 v[38:41], v[132:135], v[212:215], v[38:41]
	v_mfma_f32_16x16x32_bf16 v[34:37], v[180:183], v[212:215], v[34:37]
	v_mfma_f32_16x16x32_bf16 v[62:65], v[136:139], v[192:195], v[62:65]
	v_mfma_f32_16x16x32_bf16 v[58:61], v[184:187], v[192:195], v[58:61]
	v_mfma_f32_16x16x32_bf16 v[54:57], v[136:139], v[200:203], v[54:57]
	v_mfma_f32_16x16x32_bf16 v[50:53], v[184:187], v[200:203], v[50:53]
	v_mfma_f32_16x16x32_bf16 v[46:49], v[136:139], v[208:211], v[46:49]
	v_mfma_f32_16x16x32_bf16 v[42:45], v[184:187], v[208:211], v[42:45]
	v_mfma_f32_16x16x32_bf16 v[38:41], v[136:139], v[216:219], v[38:41]
	v_mfma_f32_16x16x32_bf16 v[34:37], v[184:187], v[216:219], v[34:37]
	v_mfma_f32_16x16x32_bf16 v[30:33], v[220:223], v[188:191], v[30:33]
	v_mfma_f32_16x16x32_bf16 v[26:29], v[246:249], v[188:191], v[26:29]
	v_mfma_f32_16x16x32_bf16 v[22:25], v[220:223], v[196:199], v[22:25]
	v_mfma_f32_16x16x32_bf16 v[18:21], v[246:249], v[196:199], v[18:21]
	v_mfma_f32_16x16x32_bf16 v[14:17], v[220:223], v[204:207], v[14:17]
	v_mfma_f32_16x16x32_bf16 v[10:13], v[246:249], v[204:207], v[10:13]
	v_mfma_f32_16x16x32_bf16 v[6:9], v[220:223], v[212:215], v[6:9]
	v_mfma_f32_16x16x32_bf16 v[2:5], v[246:249], v[212:215], v[2:5]
	v_mfma_f32_16x16x32_bf16 v[30:33], v[242:245], v[192:195], v[30:33]
	v_mfma_f32_16x16x32_bf16 v[26:29], v[250:253], v[192:195], v[26:29]
	v_mfma_f32_16x16x32_bf16 v[22:25], v[242:245], v[200:203], v[22:25]
	v_mfma_f32_16x16x32_bf16 v[18:21], v[250:253], v[200:203], v[18:21]
	v_mfma_f32_16x16x32_bf16 v[14:17], v[242:245], v[208:211], v[14:17]
	v_mfma_f32_16x16x32_bf16 v[10:13], v[250:253], v[208:211], v[10:13]
	v_mfma_f32_16x16x32_bf16 v[6:9], v[242:245], v[216:219], v[6:9]
	v_mfma_f32_16x16x32_bf16 v[2:5], v[250:253], v[216:219], v[2:5]
	s_setprio 0
	s_barrier
	ds_read_b128 v[132:135], v170
	ds_read_b128 v[136:139], v171
	ds_read_b128 v[180:183], v172
	ds_read_b128 v[184:187], v173
	v_readfirstlane_b32 s10, v149
	v_add_u32_e32 v131, s15, v142
	s_mov_b32 m0, s10
	v_readfirstlane_b32 s10, v150
	ds_read_b128 v[188:191], v157 offset:32768
	ds_read_b128 v[192:195], v157 offset:33792
	ds_read_b128 v[196:199], v157 offset:34816
	ds_read_b128 v[200:203], v157 offset:35840
	ds_read_b128 v[204:207], v157 offset:36864
	ds_read_b128 v[208:211], v157 offset:37888
	ds_read_b128 v[212:215], v157 offset:38912
	ds_read_b128 v[216:219], v157 offset:39936
	global_load_lds_dwordx4 v131, s[76:77]
	v_add_u32_e32 v131, s15, v143
	s_mov_b32 m0, s10
	s_nop 0
	global_load_lds_dwordx4 v131, s[76:77]
	ds_read_b128 v[220:223], v174
	ds_read_b128 v[242:245], v175
	ds_read_b128 v[246:249], v176
	ds_read_b128 v[250:253], v177
	s_waitcnt vmcnt(8)
	s_waitcnt lgkmcnt(0)
	s_barrier
	s_setprio 1
	v_mfma_f32_16x16x32_bf16 v[126:129], v[132:135], v[188:191], v[126:129]
	v_mfma_f32_16x16x32_bf16 v[122:125], v[180:183], v[188:191], v[122:125]
	v_mfma_f32_16x16x32_bf16 v[118:121], v[132:135], v[196:199], v[118:121]
	v_mfma_f32_16x16x32_bf16 v[114:117], v[180:183], v[196:199], v[114:117]
	v_mfma_f32_16x16x32_bf16 v[110:113], v[132:135], v[204:207], v[110:113]
	v_mfma_f32_16x16x32_bf16 v[106:109], v[180:183], v[204:207], v[106:109]
	v_mfma_f32_16x16x32_bf16 v[102:105], v[132:135], v[212:215], v[102:105]
	v_mfma_f32_16x16x32_bf16 v[98:101], v[180:183], v[212:215], v[98:101]
	v_mfma_f32_16x16x32_bf16 v[126:129], v[136:139], v[192:195], v[126:129]
	v_mfma_f32_16x16x32_bf16 v[122:125], v[184:187], v[192:195], v[122:125]
	v_mfma_f32_16x16x32_bf16 v[118:121], v[136:139], v[200:203], v[118:121]
	v_mfma_f32_16x16x32_bf16 v[114:117], v[184:187], v[200:203], v[114:117]
	v_mfma_f32_16x16x32_bf16 v[110:113], v[136:139], v[208:211], v[110:113]
	v_mfma_f32_16x16x32_bf16 v[106:109], v[184:187], v[208:211], v[106:109]
	v_mfma_f32_16x16x32_bf16 v[102:105], v[136:139], v[216:219], v[102:105]
	v_mfma_f32_16x16x32_bf16 v[98:101], v[184:187], v[216:219], v[98:101]
	v_mfma_f32_16x16x32_bf16 v[94:97], v[220:223], v[188:191], v[94:97]
	v_mfma_f32_16x16x32_bf16 v[90:93], v[246:249], v[188:191], v[90:93]
	v_mfma_f32_16x16x32_bf16 v[86:89], v[220:223], v[196:199], v[86:89]
	v_mfma_f32_16x16x32_bf16 v[82:85], v[246:249], v[196:199], v[82:85]
	v_mfma_f32_16x16x32_bf16 v[78:81], v[220:223], v[204:207], v[78:81]
	v_mfma_f32_16x16x32_bf16 v[74:77], v[246:249], v[204:207], v[74:77]
	v_mfma_f32_16x16x32_bf16 v[70:73], v[220:223], v[212:215], v[70:73]
	v_mfma_f32_16x16x32_bf16 v[66:69], v[246:249], v[212:215], v[66:69]
	v_mfma_f32_16x16x32_bf16 v[94:97], v[242:245], v[192:195], v[94:97]
	v_mfma_f32_16x16x32_bf16 v[90:93], v[250:253], v[192:195], v[90:93]
	v_mfma_f32_16x16x32_bf16 v[86:89], v[242:245], v[200:203], v[86:89]
	v_mfma_f32_16x16x32_bf16 v[82:85], v[250:253], v[200:203], v[82:85]
	v_mfma_f32_16x16x32_bf16 v[78:81], v[242:245], v[208:211], v[78:81]
	v_mfma_f32_16x16x32_bf16 v[74:77], v[250:253], v[208:211], v[74:77]
	v_mfma_f32_16x16x32_bf16 v[70:73], v[242:245], v[216:219], v[70:73]
	v_mfma_f32_16x16x32_bf16 v[66:69], v[250:253], v[216:219], v[66:69]
	s_setprio 0
	s_barrier
; #define EPI_SCHED __builtin_amdgcn_sched_barrier(0)
; DI void gemm_resid(const u16* A, const u16* Bt, int K, const float* xin, float* xout, int bid, int nb, int tid) {
;     ...
; #pragma unroll
;     for (int ai = 0; ai < 2; ++ai)
; #pragma unroll
;       for (int bj = 0; bj < 2; ++bj) {
;         float4 xi[4][2];
; #pragma unroll
;         for (int m = 0; m < 4; ++m)
; #pragma unroll
;           for (int n = 0; n < 2; ++n) xi[m][n] = *reinterpret_cast<const float4*>(xin + (size_t)ACC_ROW * 2048 + ACC_COL);
; #pragma unroll
;         for (int m = 0; m < 4; ++m)
; #pragma unroll
;           for (int n = 0; n < 2; ++n) {
;             const f32x4 v = acc[ai][bj][m][n];
;             float4 r; r.x = xi[m][n].x + v[0]; r.y = xi[m][n].y + v[1]; r.z = xi[m][n].z + v[2]; r.w = xi[m][n].w + v[3];
;             *reinterpret_cast<float4*>(xout + (size_t)ACC_ROW * 2048 + ACC_COL) = r;
;           }
;         EPI_SCHED;
;       }
	v_readfirstlane_b32 s10, v151
	v_add_u32_e32 v131, s19, v142
	s_mov_b32 m0, s10
	v_readfirstlane_b32 s10, v152
	global_load_lds_dwordx4 v131, s[78:79]
	v_add_u32_e32 v131, s19, v143
	s_mov_b32 m0, s10
	s_nop 0
	global_load_lds_dwordx4 v131, s[78:79]
	v_readfirstlane_b32 s10, v153
	v_add_u32_e32 v131, s13, v142
	s_mov_b32 m0, s10
	v_readfirstlane_b32 s10, v154
	ds_read_b128 v[188:191], v157 offset:49152
	ds_read_b128 v[192:195], v157 offset:50176
	ds_read_b128 v[196:199], v157 offset:51200
	ds_read_b128 v[200:203], v157 offset:52224
	ds_read_b128 v[204:207], v157 offset:53248
	ds_read_b128 v[208:211], v157 offset:54272
	ds_read_b128 v[212:215], v157 offset:55296
	ds_read_b128 v[216:219], v157 offset:56320
	global_load_lds_dwordx4 v131, s[76:77]
	v_add_u32_e32 v131, s13, v143
	s_mov_b32 m0, s10
	s_nop 0
	global_load_lds_dwordx4 v131, s[76:77]
	v_readfirstlane_b32 s10, v155
	v_add_u32_e32 v131, s12, v142
	s_mov_b32 m0, s10
	v_readfirstlane_b32 s10, v156
	global_load_lds_dwordx4 v131, s[78:79]
	v_add_u32_e32 v131, s12, v143
	s_mov_b32 m0, s10
	s_nop 0
	global_load_lds_dwordx4 v131, s[78:79]
	s_waitcnt vmcnt(8)
	s_waitcnt lgkmcnt(0)
	s_barrier
	s_setprio 1
	v_mfma_f32_16x16x32_bf16 v[62:65], v[132:135], v[188:191], v[62:65]
	v_mfma_f32_16x16x32_bf16 v[58:61], v[180:183], v[188:191], v[58:61]
	v_mfma_f32_16x16x32_bf16 v[54:57], v[132:135], v[196:199], v[54:57]
	v_mfma_f32_16x16x32_bf16 v[50:53], v[180:183], v[196:199], v[50:53]
	v_mfma_f32_16x16x32_bf16 v[46:49], v[132:135], v[204:207], v[46:49]
	v_mfma_f32_16x16x32_bf16 v[42:45], v[180:183], v[204:207], v[42:45]
	v_mfma_f32_16x16x32_bf16 v[38:41], v[132:135], v[212:215], v[38:41]
	v_mfma_f32_16x16x32_bf16 v[34:37], v[180:183], v[212:215], v[34:37]
	v_mfma_f32_16x16x32_bf16 v[62:65], v[136:139], v[192:195], v[62:65]
	v_mfma_f32_16x16x32_bf16 v[58:61], v[184:187], v[192:195], v[58:61]
	v_mfma_f32_16x16x32_bf16 v[54:57], v[136:139], v[200:203], v[54:57]
	v_mfma_f32_16x16x32_bf16 v[50:53], v[184:187], v[200:203], v[50:53]
	v_mfma_f32_16x16x32_bf16 v[46:49], v[136:139], v[208:211], v[46:49]
	v_mfma_f32_16x16x32_bf16 v[42:45], v[184:187], v[208:211], v[42:45]
	v_mfma_f32_16x16x32_bf16 v[38:41], v[136:139], v[216:219], v[38:41]
	v_mfma_f32_16x16x32_bf16 v[34:37], v[184:187], v[216:219], v[34:37]
	v_mfma_f32_16x16x32_bf16 v[30:33], v[220:223], v[188:191], v[30:33]
	v_mfma_f32_16x16x32_bf16 v[26:29], v[246:249], v[188:191], v[26:29]
	v_mfma_f32_16x16x32_bf16 v[22:25], v[220:223], v[196:199], v[22:25]
	v_mfma_f32_16x16x32_bf16 v[18:21], v[246:249], v[196:199], v[18:21]
	v_mfma_f32_16x16x32_bf16 v[14:17], v[220:223], v[204:207], v[14:17]
	v_mfma_f32_16x16x32_bf16 v[10:13], v[246:249], v[204:207], v[10:13]
	v_mfma_f32_16x16x32_bf16 v[6:9], v[220:223], v[212:215], v[6:9]
	v_mfma_f32_16x16x32_bf16 v[2:5], v[246:249], v[212:215], v[2:5]
	v_mfma_f32_16x16x32_bf16 v[30:33], v[242:245], v[192:195], v[30:33]
	v_mfma_f32_16x16x32_bf16 v[26:29], v[250:253], v[192:195], v[26:29]
	v_mfma_f32_16x16x32_bf16 v[22:25], v[242:245], v[200:203], v[22:25]
	v_mfma_f32_16x16x32_bf16 v[18:21], v[250:253], v[200:203], v[18:21]
	v_mfma_f32_16x16x32_bf16 v[14:17], v[242:245], v[208:211], v[14:17]
	v_mfma_f32_16x16x32_bf16 v[10:13], v[250:253], v[208:211], v[10:13]
	v_mfma_f32_16x16x32_bf16 v[6:9], v[242:245], v[216:219], v[6:9]
	v_mfma_f32_16x16x32_bf16 v[2:5], v[250:253], v[216:219], v[2:5]
	s_setprio 0
	v_add_u32_e32 v130, 0x100, v130
	s_mov_b32 s10, s11
	s_barrier
	s_cbranch_scc0 .LBB0_32
	v_mov_b32_e32 v131, v239
	s_nop 0
	v_ashrrev_i32_e32 v130, 2, v131
	v_and_b32_e32 v130, 0xffffffc0, v130
	v_and_or_b32 v132, v131, 15, s8
	v_add_u32_e32 v130, v132, v130
	v_lshrrev_b32_e32 v132, 1, v131
	v_lshrrev_b32_e32 v131, 2, v131
	v_and_b32_e32 v132, 0x60, v132
	v_and_b32_e32 v131, 12, v131
	v_or3_b32 v132, v132, v131, s7
	v_ashrrev_i32_e32 v131, 31, v130
	v_ashrrev_i32_e32 v133, 31, v132
	v_lshlrev_b64 v[134:135], 13, v[130:131]
	v_lshl_add_u64 v[134:135], s[72:73], 0, v[134:135]
	v_lshlrev_b64 v[132:133], 2, v[132:133]
	v_lshl_add_u64 v[140:141], v[134:135], 0, v[132:133]
	global_load_dwordx4 v[180:183], v[140:141], off
	v_or_b32_e32 v134, 16, v130
	v_ashrrev_i32_e32 v135, 31, v134
	v_lshlrev_b64 v[134:135], 13, v[134:135]
	v_lshl_add_u64 v[134:135], s[72:73], 0, v[134:135]
	v_lshl_add_u64 v[138:139], v[134:135], 0, v[132:133]
	v_or_b32_e32 v134, 32, v130
	v_ashrrev_i32_e32 v135, 31, v134
	v_lshlrev_b64 v[134:135], 13, v[134:135]
	v_lshl_add_u64 v[134:135], s[72:73], 0, v[134:135]
	v_lshl_add_u64 v[136:137], v[134:135], 0, v[132:133]
	v_or_b32_e32 v134, 48, v130
	v_ashrrev_i32_e32 v135, 31, v134
	v_lshlrev_b64 v[134:135], 13, v[134:135]
	v_lshl_add_u64 v[134:135], s[72:73], 0, v[134:135]
	v_lshl_add_u64 v[134:135], v[134:135], 0, v[132:133]
	s_waitcnt vmcnt(0)
	v_pk_add_f32 v[126:127], v[126:127], v[180:181]
	v_pk_add_f32 v[128:129], v[128:129], v[182:183]
	global_store_dwordx4 v[140:141], v[126:129], off
	global_load_dwordx4 v[126:129], v[140:141], off offset:64
	s_waitcnt vmcnt(0)
	v_pk_add_f32 v[122:123], v[122:123], v[126:127]
	v_pk_add_f32 v[124:125], v[124:125], v[128:129]
	global_store_dwordx4 v[140:141], v[122:125], off offset:64
	global_load_dwordx4 v[122:125], v[138:139], off
	s_waitcnt vmcnt(0)
	v_pk_add_f32 v[118:119], v[118:119], v[122:123]
	v_pk_add_f32 v[120:121], v[120:121], v[124:125]
	global_store_dwordx4 v[138:139], v[118:121], off
	global_load_dwordx4 v[118:121], v[138:139], off offset:64
	s_waitcnt vmcnt(0)
	v_pk_add_f32 v[114:115], v[114:115], v[118:119]
	v_pk_add_f32 v[116:117], v[116:117], v[120:121]
	global_store_dwordx4 v[138:139], v[114:117], off offset:64
	global_load_dwordx4 v[114:117], v[136:137], off
	s_waitcnt vmcnt(0)
; #define WAIT_V(n) asm volatile("s_waitcnt vmcnt(" #n ")" ::: "memory")
; #define BAR __builtin_amdgcn_s_barrier()
; #define EPI_SCHED __builtin_amdgcn_sched_barrier(0)
; template <class EPI>
; DI void gemm_stream(const u16* __restrict__ A, const u16* __restrict__ Bt, const int K, const int nM, const int nN,
;                     const int bid, const int nb, const int tid, EPI epi) {
;     ...
;     brow = brow2; bcol = bcol2; pm = pm2; pn = pn2;
;   }
;   WAIT_V(0);
;   if (wr == 0) BAR;
;   BAR;
; DI void gemm_resid(const u16* A, const u16* Bt, int K, const float* xin, float* xout, int bid, int nb, int tid) {
;     ...
; #pragma unroll
;     for (int ai = 0; ai < 2; ++ai)
; #pragma unroll
;       for (int bj = 0; bj < 2; ++bj) {
;         float4 xi[4][2];
; #pragma unroll
;         for (int m = 0; m < 4; ++m)
; #pragma unroll
;           for (int n = 0; n < 2; ++n) xi[m][n] = *reinterpret_cast<const float4*>(xin + (size_t)ACC_ROW * 2048 + ACC_COL);
; #pragma unroll
;         for (int m = 0; m < 4; ++m)
; #pragma unroll
;           for (int n = 0; n < 2; ++n) {
;             const f32x4 v = acc[ai][bj][m][n];
;             float4 r; r.x = xi[m][n].x + v[0]; r.y = xi[m][n].y + v[1]; r.z = xi[m][n].z + v[2]; r.w = xi[m][n].w + v[3];
;             *reinterpret_cast<float4*>(xout + (size_t)ACC_ROW * 2048 + ACC_COL) = r;
;           }
;         EPI_SCHED;
;       }
	v_pk_add_f32 v[110:111], v[110:111], v[114:115]
	v_pk_add_f32 v[112:113], v[112:113], v[116:117]
	global_store_dwordx4 v[136:137], v[110:113], off
	global_load_dwordx4 v[110:113], v[136:137], off offset:64
	s_waitcnt vmcnt(0)
	v_pk_add_f32 v[106:107], v[106:107], v[110:111]
	v_pk_add_f32 v[108:109], v[108:109], v[112:113]
	global_store_dwordx4 v[136:137], v[106:109], off offset:64
	global_load_dwordx4 v[106:109], v[134:135], off
	s_waitcnt vmcnt(0)
	v_pk_add_f32 v[102:103], v[102:103], v[106:107]
	v_pk_add_f32 v[104:105], v[104:105], v[108:109]
	global_store_dwordx4 v[134:135], v[102:105], off
	global_load_dwordx4 v[102:105], v[134:135], off offset:64
	s_waitcnt vmcnt(0)
	v_pk_add_f32 v[98:99], v[98:99], v[102:103]
	v_pk_add_f32 v[100:101], v[100:101], v[104:105]
	global_store_dwordx4 v[134:135], v[98:101], off offset:64
	global_load_dwordx4 v[98:101], v[140:141], off offset:512
	s_waitcnt vmcnt(0)
	v_pk_add_f32 v[94:95], v[94:95], v[98:99]
	v_pk_add_f32 v[96:97], v[96:97], v[100:101]
	global_store_dwordx4 v[140:141], v[94:97], off offset:512
	global_load_dwordx4 v[94:97], v[140:141], off offset:576
	s_waitcnt vmcnt(0)
	v_pk_add_f32 v[90:91], v[90:91], v[94:95]
	v_pk_add_f32 v[92:93], v[92:93], v[96:97]
	global_store_dwordx4 v[140:141], v[90:93], off offset:576
	global_load_dwordx4 v[90:93], v[138:139], off offset:512
	s_waitcnt vmcnt(0)
	v_pk_add_f32 v[86:87], v[86:87], v[90:91]
	v_pk_add_f32 v[88:89], v[88:89], v[92:93]
	global_store_dwordx4 v[138:139], v[86:89], off offset:512
	global_load_dwordx4 v[86:89], v[138:139], off offset:576
	s_waitcnt vmcnt(0)
	v_pk_add_f32 v[82:83], v[82:83], v[86:87]
	v_pk_add_f32 v[84:85], v[84:85], v[88:89]
	global_store_dwordx4 v[138:139], v[82:85], off offset:576
	global_load_dwordx4 v[82:85], v[136:137], off offset:512
	s_waitcnt vmcnt(0)
	v_pk_add_f32 v[78:79], v[78:79], v[82:83]
	v_pk_add_f32 v[80:81], v[80:81], v[84:85]
	global_store_dwordx4 v[136:137], v[78:81], off offset:512
	global_load_dwordx4 v[78:81], v[136:137], off offset:576
	s_waitcnt vmcnt(0)
	v_pk_add_f32 v[74:75], v[74:75], v[78:79]
	v_pk_add_f32 v[76:77], v[76:77], v[80:81]
	global_store_dwordx4 v[136:137], v[74:77], off offset:576
	global_load_dwordx4 v[74:77], v[134:135], off offset:512
	s_waitcnt vmcnt(0)
	v_pk_add_f32 v[70:71], v[70:71], v[74:75]
	v_pk_add_f32 v[72:73], v[72:73], v[76:77]
	global_store_dwordx4 v[134:135], v[70:73], off offset:512
	global_load_dwordx4 v[70:73], v[134:135], off offset:576
	s_waitcnt vmcnt(0)
	v_pk_add_f32 v[66:67], v[66:67], v[70:71]
	v_pk_add_f32 v[68:69], v[68:69], v[72:73]
	global_store_dwordx4 v[134:135], v[66:69], off offset:576
	s_nop 1
	v_add_u32_e32 v66, 0x80, v130
	v_ashrrev_i32_e32 v67, 31, v66
	v_lshlrev_b64 v[66:67], 13, v[66:67]
	v_lshl_add_u64 v[66:67], s[72:73], 0, v[66:67]
	v_lshl_add_u64 v[72:73], v[66:67], 0, v[132:133]
	global_load_dwordx4 v[74:77], v[72:73], off
	v_add_u32_e32 v66, 0x90, v130
	v_ashrrev_i32_e32 v67, 31, v66
	v_lshlrev_b64 v[66:67], 13, v[66:67]
	v_lshl_add_u64 v[66:67], s[72:73], 0, v[66:67]
	v_lshl_add_u64 v[70:71], v[66:67], 0, v[132:133]
	v_add_u32_e32 v66, 0xa0, v130
	v_ashrrev_i32_e32 v67, 31, v66
	v_lshlrev_b64 v[66:67], 13, v[66:67]
	v_lshl_add_u64 v[66:67], s[72:73], 0, v[66:67]
	v_lshl_add_u64 v[68:69], v[66:67], 0, v[132:133]
	v_add_u32_e32 v66, 0xb0, v130
	v_ashrrev_i32_e32 v67, 31, v66
	v_lshlrev_b64 v[66:67], 13, v[66:67]
	v_lshl_add_u64 v[66:67], s[72:73], 0, v[66:67]
	v_lshl_add_u64 v[66:67], v[66:67], 0, v[132:133]
	s_waitcnt vmcnt(0)
	v_pk_add_f32 v[62:63], v[62:63], v[74:75]
	v_pk_add_f32 v[64:65], v[64:65], v[76:77]
	global_store_dwordx4 v[72:73], v[62:65], off
	global_load_dwordx4 v[62:65], v[72:73], off offset:64
	s_waitcnt vmcnt(0)
	v_pk_add_f32 v[58:59], v[58:59], v[62:63]
	v_pk_add_f32 v[60:61], v[60:61], v[64:65]
	global_store_dwordx4 v[72:73], v[58:61], off offset:64
	global_load_dwordx4 v[58:61], v[70:71], off
	s_waitcnt vmcnt(0)
	v_pk_add_f32 v[54:55], v[54:55], v[58:59]
	v_pk_add_f32 v[56:57], v[56:57], v[60:61]
	global_store_dwordx4 v[70:71], v[54:57], off
	global_load_dwordx4 v[54:57], v[70:71], off offset:64
	s_waitcnt vmcnt(0)
	v_pk_add_f32 v[50:51], v[50:51], v[54:55]
	v_pk_add_f32 v[52:53], v[52:53], v[56:57]
	global_store_dwordx4 v[70:71], v[50:53], off offset:64
	global_load_dwordx4 v[50:53], v[68:69], off
	s_waitcnt vmcnt(0)
	v_pk_add_f32 v[46:47], v[46:47], v[50:51]
	v_pk_add_f32 v[48:49], v[48:49], v[52:53]
	global_store_dwordx4 v[68:69], v[46:49], off
	global_load_dwordx4 v[46:49], v[68:69], off offset:64
	s_waitcnt vmcnt(0)
	v_pk_add_f32 v[42:43], v[42:43], v[46:47]
	v_pk_add_f32 v[44:45], v[44:45], v[48:49]
	global_store_dwordx4 v[68:69], v[42:45], off offset:64
	global_load_dwordx4 v[42:45], v[66:67], off
	s_waitcnt vmcnt(0)
	v_pk_add_f32 v[38:39], v[38:39], v[42:43]
	v_pk_add_f32 v[40:41], v[40:41], v[44:45]
	global_store_dwordx4 v[66:67], v[38:41], off
	global_load_dwordx4 v[38:41], v[66:67], off offset:64
	s_waitcnt vmcnt(0)
	v_pk_add_f32 v[34:35], v[34:35], v[38:39]
	v_pk_add_f32 v[36:37], v[36:37], v[40:41]
	global_store_dwordx4 v[66:67], v[34:37], off offset:64
	global_load_dwordx4 v[34:37], v[72:73], off offset:512
	s_waitcnt vmcnt(0)
	v_pk_add_f32 v[30:31], v[30:31], v[34:35]
	v_pk_add_f32 v[32:33], v[32:33], v[36:37]
	global_store_dwordx4 v[72:73], v[30:33], off offset:512
	global_load_dwordx4 v[30:33], v[72:73], off offset:576
	s_waitcnt vmcnt(0)
	v_pk_add_f32 v[26:27], v[26:27], v[30:31]
	v_pk_add_f32 v[28:29], v[28:29], v[32:33]
	global_store_dwordx4 v[72:73], v[26:29], off offset:576
	global_load_dwordx4 v[26:29], v[70:71], off offset:512
	s_waitcnt vmcnt(0)
	v_pk_add_f32 v[22:23], v[22:23], v[26:27]
	v_pk_add_f32 v[24:25], v[24:25], v[28:29]
	global_store_dwordx4 v[70:71], v[22:25], off offset:512
	global_load_dwordx4 v[22:25], v[70:71], off offset:576
	s_waitcnt vmcnt(0)
	v_pk_add_f32 v[18:19], v[18:19], v[22:23]
	v_pk_add_f32 v[20:21], v[20:21], v[24:25]
	global_store_dwordx4 v[70:71], v[18:21], off offset:576
	global_load_dwordx4 v[18:21], v[68:69], off offset:512
	s_waitcnt vmcnt(0)
	v_pk_add_f32 v[14:15], v[14:15], v[18:19]
	v_pk_add_f32 v[16:17], v[16:17], v[20:21]
	global_store_dwordx4 v[68:69], v[14:17], off offset:512
	global_load_dwordx4 v[14:17], v[68:69], off offset:576
	s_waitcnt vmcnt(0)
	v_pk_add_f32 v[10:11], v[10:11], v[14:15]
	v_pk_add_f32 v[12:13], v[12:13], v[16:17]
	global_store_dwordx4 v[68:69], v[10:13], off offset:576
	global_load_dwordx4 v[10:13], v[66:67], off offset:512
	s_waitcnt vmcnt(0)
	v_pk_add_f32 v[6:7], v[6:7], v[10:11]
	v_pk_add_f32 v[8:9], v[8:9], v[12:13]
	global_store_dwordx4 v[66:67], v[6:9], off offset:512
	global_load_dwordx4 v[6:9], v[66:67], off offset:576
	s_waitcnt vmcnt(0)
	v_pk_add_f32 v[2:3], v[2:3], v[6:7]
	v_pk_add_f32 v[4:5], v[4:5], v[8:9]
	global_store_dwordx4 v[66:67], v[2:5], off offset:576
	s_and_b64 vcc, exec, s[0:1]
	s_mov_b32 s8, s5
	s_mov_b32 s7, s6
	s_cbranch_vccz .LBB0_29
	s_waitcnt vmcnt(0)
	s_movk_i32 s0, 0x100
	v_cmp_gt_u32_e32 vcc, s0, v239
	s_and_saveexec_b64 s[0:1], vcc
	s_cbranch_execz .LBB0_36
	s_barrier

.LBB0_46:
	v_or_b32_e32 v149, 0x10000, v146
	v_add_u32_e32 v154, 0x10400, v146
	ds_read_b128 v[150:153], v149
	ds_read_b128 v[154:157], v154
	v_add_u32_e32 v149, 0x10800, v146
	v_add_u32_e32 v162, 0x10c00, v146
	ds_read_b128 v[158:161], v149
	ds_read_b128 v[166:169], v162
	s_add_i32 s11, s10, -2
	s_cmp_lt_u32 s11, 30
	s_cselect_b32 s12, s9, s6
	s_cselect_b32 s13, s8, s5
	v_add_u32_e32 v162, 0xc000, v0
	v_add_u32_e32 v149, 0xfffc0000, v148
	v_readfirstlane_b32 s14, v162
	s_mov_b32 m0, s14
	ds_read_b128 v[170:173], v145
	ds_read_b128 v[174:177], v145 offset:1024
	ds_read_b128 v[180:183], v145 offset:2048
	ds_read_b128 v[184:187], v145 offset:3072
	ds_read_b128 v[188:191], v145 offset:4096
	ds_read_b128 v[192:195], v145 offset:5120
	ds_read_b128 v[196:199], v145 offset:6144
	ds_read_b128 v[200:203], v145 offset:7168
	global_load_lds_dwordx4 v149, s[80:81]
	v_add_u32_e32 v149, 0xe000, v0
	s_nop 0
	v_readfirstlane_b32 s14, v149
	s_mov_b32 m0, s14
	s_nop 0
	global_load_lds_dwordx4 v148, s[80:81]
	v_or_b32_e32 v149, 0x14000, v146
	v_add_u32_e32 v162, 0x14400, v146
	ds_read_b128 v[204:207], v149
	ds_read_b128 v[208:211], v162
	v_add_u32_e32 v149, 0x14800, v146
	v_add_u32_e32 v162, 0x14c00, v146
	ds_read_b128 v[212:215], v149
	ds_read_b128 v[216:219], v162
	s_waitcnt vmcnt(8)
	s_waitcnt lgkmcnt(0)
	s_barrier
	s_setprio 1
	v_mfma_f32_16x16x32_bf16 v[126:129], v[150:153], v[170:173], v[126:129]
	v_mfma_f32_16x16x32_bf16 v[118:121], v[158:161], v[170:173], v[118:121]
	v_mfma_f32_16x16x32_bf16 v[110:113], v[150:153], v[180:183], v[110:113]
	v_mfma_f32_16x16x32_bf16 v[102:105], v[158:161], v[180:183], v[102:105]
	v_mfma_f32_16x16x32_bf16 v[94:97], v[150:153], v[188:191], v[94:97]
	v_mfma_f32_16x16x32_bf16 v[86:89], v[158:161], v[188:191], v[86:89]
	v_mfma_f32_16x16x32_bf16 v[78:81], v[150:153], v[196:199], v[78:81]
	v_mfma_f32_16x16x32_bf16 v[70:73], v[158:161], v[196:199], v[70:73]
	v_mfma_f32_16x16x32_bf16 v[126:129], v[154:157], v[174:177], v[126:129]
	v_mfma_f32_16x16x32_bf16 v[118:121], v[166:169], v[174:177], v[118:121]
	v_mfma_f32_16x16x32_bf16 v[110:113], v[154:157], v[184:187], v[110:113]
	v_mfma_f32_16x16x32_bf16 v[102:105], v[166:169], v[184:187], v[102:105]
	v_mfma_f32_16x16x32_bf16 v[94:97], v[154:157], v[192:195], v[94:97]
	v_mfma_f32_16x16x32_bf16 v[86:89], v[166:169], v[192:195], v[86:89]
	v_mfma_f32_16x16x32_bf16 v[78:81], v[154:157], v[200:203], v[78:81]
	v_mfma_f32_16x16x32_bf16 v[70:73], v[166:169], v[200:203], v[70:73]
	v_mfma_f32_16x16x32_bf16 v[122:125], v[204:207], v[170:173], v[122:125]
	v_mfma_f32_16x16x32_bf16 v[114:117], v[212:215], v[170:173], v[114:117]
	v_mfma_f32_16x16x32_bf16 v[106:109], v[204:207], v[180:183], v[106:109]
	v_mfma_f32_16x16x32_bf16 v[98:101], v[212:215], v[180:183], v[98:101]
	v_mfma_f32_16x16x32_bf16 v[90:93], v[204:207], v[188:191], v[90:93]
	v_mfma_f32_16x16x32_bf16 v[82:85], v[212:215], v[188:191], v[82:85]
	v_mfma_f32_16x16x32_bf16 v[74:77], v[204:207], v[196:199], v[74:77]
	v_mfma_f32_16x16x32_bf16 v[66:69], v[212:215], v[196:199], v[66:69]
	v_mfma_f32_16x16x32_bf16 v[122:125], v[208:211], v[174:177], v[122:125]
	v_mfma_f32_16x16x32_bf16 v[114:117], v[216:219], v[174:177], v[114:117]
	v_mfma_f32_16x16x32_bf16 v[106:109], v[208:211], v[184:187], v[106:109]
	v_mfma_f32_16x16x32_bf16 v[98:101], v[216:219], v[184:187], v[98:101]
	v_mfma_f32_16x16x32_bf16 v[90:93], v[208:211], v[192:195], v[90:93]
	v_mfma_f32_16x16x32_bf16 v[82:85], v[216:219], v[192:195], v[82:85]
	v_mfma_f32_16x16x32_bf16 v[74:77], v[208:211], v[200:203], v[74:77]
	v_mfma_f32_16x16x32_bf16 v[66:69], v[216:219], v[200:203], v[66:69]
	s_setprio 0
	s_barrier
	s_cselect_b32 s14, s10, 0
	s_lshl_b32 s12, s12, 11
	s_lshl_b32 s15, s14, 6
	s_or_b32 s16, s12, s15
	s_lshl_b32 s16, s16, 1
	v_readfirstlane_b32 s17, v132
	v_add_u32_e32 v149, s16, v130
	s_mov_b32 m0, s17
	s_nop 0
	global_load_lds_dwordx4 v149, s[82:83]
	v_add_u32_e32 v149, s16, v131
	v_readfirstlane_b32 s16, v133
	s_mov_b32 m0, s16
	s_nop 0
	global_load_lds_dwordx4 v149, s[82:83]
	s_lshl_b32 s16, s13, 11
	s_or_b32 s17, s16, s15
	s_lshl_b32 s17, s17, 1
	v_readfirstlane_b32 s18, v0
	v_add_u32_e32 v149, s17, v130
	s_mov_b32 m0, s18
	ds_read_b128 v[170:173], v145 offset:16384
	ds_read_b128 v[174:177], v145 offset:17408
	ds_read_b128 v[180:183], v145 offset:18432
	ds_read_b128 v[184:187], v145 offset:19456
	ds_read_b128 v[188:191], v145 offset:20480
	ds_read_b128 v[192:195], v145 offset:21504
	ds_read_b128 v[196:199], v145 offset:22528
	ds_read_b128 v[200:203], v145 offset:23552
	global_load_lds_dwordx4 v149, s[80:81]
	v_add_u32_e32 v149, s17, v131
	v_readfirstlane_b32 s17, v134
	s_mov_b32 m0, s17
	s_nop 0
	global_load_lds_dwordx4 v149, s[80:81]
	s_or_b32 s17, s12, 0x40000
	s_or_b32 s18, s17, s15
	s_lshl_b32 s18, s18, 1
	v_readfirstlane_b32 s19, v135
	v_add_u32_e32 v149, s18, v130
	s_mov_b32 m0, s19
	s_nop 0
	global_load_lds_dwordx4 v149, s[82:83]
	v_add_u32_e32 v149, s18, v131
	v_readfirstlane_b32 s18, v136
	s_mov_b32 m0, s18
	s_nop 0
	global_load_lds_dwordx4 v149, s[82:83]
	s_waitcnt vmcnt(8)
	s_waitcnt lgkmcnt(0)
	s_barrier
	s_setprio 1
	v_mfma_f32_16x16x32_bf16 v[62:65], v[150:153], v[170:173], v[62:65]
	v_mfma_f32_16x16x32_bf16 v[54:57], v[158:161], v[170:173], v[54:57]
	v_mfma_f32_16x16x32_bf16 v[46:49], v[150:153], v[180:183], v[46:49]
	v_mfma_f32_16x16x32_bf16 v[38:41], v[158:161], v[180:183], v[38:41]
	v_mfma_f32_16x16x32_bf16 v[30:33], v[150:153], v[188:191], v[30:33]
	v_mfma_f32_16x16x32_bf16 v[22:25], v[158:161], v[188:191], v[22:25]
	v_mfma_f32_16x16x32_bf16 v[14:17], v[150:153], v[196:199], v[14:17]
	v_mfma_f32_16x16x32_bf16 v[6:9], v[158:161], v[196:199], v[6:9]
	v_mfma_f32_16x16x32_bf16 v[62:65], v[154:157], v[174:177], v[62:65]
	v_mfma_f32_16x16x32_bf16 v[54:57], v[166:169], v[174:177], v[54:57]
	v_mfma_f32_16x16x32_bf16 v[46:49], v[154:157], v[184:187], v[46:49]
	v_mfma_f32_16x16x32_bf16 v[38:41], v[166:169], v[184:187], v[38:41]
	v_mfma_f32_16x16x32_bf16 v[30:33], v[154:157], v[192:195], v[30:33]
	v_mfma_f32_16x16x32_bf16 v[22:25], v[166:169], v[192:195], v[22:25]
	v_mfma_f32_16x16x32_bf16 v[14:17], v[154:157], v[200:203], v[14:17]
	v_mfma_f32_16x16x32_bf16 v[6:9], v[166:169], v[200:203], v[6:9]
	v_mfma_f32_16x16x32_bf16 v[58:61], v[204:207], v[170:173], v[58:61]
	v_mfma_f32_16x16x32_bf16 v[50:53], v[212:215], v[170:173], v[50:53]
	v_mfma_f32_16x16x32_bf16 v[42:45], v[204:207], v[180:183], v[42:45]
	v_mfma_f32_16x16x32_bf16 v[34:37], v[212:215], v[180:183], v[34:37]
	v_mfma_f32_16x16x32_bf16 v[26:29], v[204:207], v[188:191], v[26:29]
	v_mfma_f32_16x16x32_bf16 v[18:21], v[212:215], v[188:191], v[18:21]
	v_mfma_f32_16x16x32_bf16 v[10:13], v[204:207], v[196:199], v[10:13]
	v_mfma_f32_16x16x32_bf16 v[2:5], v[212:215], v[196:199], v[2:5]
	v_mfma_f32_16x16x32_bf16 v[58:61], v[208:211], v[174:177], v[58:61]
	v_mfma_f32_16x16x32_bf16 v[50:53], v[216:219], v[174:177], v[50:53]
	v_mfma_f32_16x16x32_bf16 v[42:45], v[208:211], v[184:187], v[42:45]
	v_mfma_f32_16x16x32_bf16 v[34:37], v[216:219], v[184:187], v[34:37]
	v_mfma_f32_16x16x32_bf16 v[26:29], v[208:211], v[192:195], v[26:29]
	v_mfma_f32_16x16x32_bf16 v[18:21], v[216:219], v[192:195], v[18:21]
	v_mfma_f32_16x16x32_bf16 v[10:13], v[208:211], v[200:203], v[10:13]
	v_mfma_f32_16x16x32_bf16 v[2:5], v[216:219], v[200:203], v[2:5]
	s_setprio 0
	s_barrier
	v_or_b32_e32 v149, 0x18000, v146
	v_add_u32_e32 v154, 0x18400, v146
	ds_read_b128 v[150:153], v149
	ds_read_b128 v[154:157], v154
	v_add_u32_e32 v149, 0x18800, v146
	v_add_u32_e32 v162, 0x18c00, v146
	ds_read_b128 v[158:161], v149
	ds_read_b128 v[166:169], v162
	s_lshl_b32 s13, s13, 12
	s_lshl_b32 s14, s14, 7
	s_add_i32 s13, s14, s13
	s_add_i32 s13, s13, 0x80000
	v_readfirstlane_b32 s14, v137
	v_add_u32_e32 v149, s13, v130
	s_mov_b32 m0, s14
	ds_read_b128 v[170:173], v145 offset:32768
	ds_read_b128 v[174:177], v145 offset:33792
	ds_read_b128 v[180:183], v145 offset:34816
	ds_read_b128 v[184:187], v145 offset:35840
	ds_read_b128 v[188:191], v145 offset:36864
	ds_read_b128 v[192:195], v145 offset:37888
	ds_read_b128 v[196:199], v145 offset:38912
	ds_read_b128 v[200:203], v145 offset:39936
	global_load_lds_dwordx4 v149, s[80:81]
	v_add_u32_e32 v149, s13, v131
	v_readfirstlane_b32 s13, v138
	s_mov_b32 m0, s13
	s_nop 0
	global_load_lds_dwordx4 v149, s[80:81]
	v_or_b32_e32 v149, 0x1c000, v146
	v_add_u32_e32 v162, 0x1c400, v146
	ds_read_b128 v[204:207], v149
	ds_read_b128 v[208:211], v162
	v_add_u32_e32 v149, 0x1c800, v146
	v_add_u32_e32 v162, 0x1cc00, v146
	ds_read_b128 v[212:215], v149
	ds_read_b128 v[216:219], v162
	s_waitcnt vmcnt(8)
	s_waitcnt lgkmcnt(0)
	s_barrier
	s_setprio 1
	v_mfma_f32_16x16x32_bf16 v[126:129], v[150:153], v[170:173], v[126:129]
	v_mfma_f32_16x16x32_bf16 v[118:121], v[158:161], v[170:173], v[118:121]
	v_mfma_f32_16x16x32_bf16 v[110:113], v[150:153], v[180:183], v[110:113]
	v_mfma_f32_16x16x32_bf16 v[102:105], v[158:161], v[180:183], v[102:105]
	v_mfma_f32_16x16x32_bf16 v[94:97], v[150:153], v[188:191], v[94:97]
	v_mfma_f32_16x16x32_bf16 v[86:89], v[158:161], v[188:191], v[86:89]
	v_mfma_f32_16x16x32_bf16 v[78:81], v[150:153], v[196:199], v[78:81]
	v_mfma_f32_16x16x32_bf16 v[70:73], v[158:161], v[196:199], v[70:73]
	v_mfma_f32_16x16x32_bf16 v[126:129], v[154:157], v[174:177], v[126:129]
	v_mfma_f32_16x16x32_bf16 v[118:121], v[166:169], v[174:177], v[118:121]
	v_mfma_f32_16x16x32_bf16 v[110:113], v[154:157], v[184:187], v[110:113]
	v_mfma_f32_16x16x32_bf16 v[102:105], v[166:169], v[184:187], v[102:105]
	v_mfma_f32_16x16x32_bf16 v[94:97], v[154:157], v[192:195], v[94:97]
	v_mfma_f32_16x16x32_bf16 v[86:89], v[166:169], v[192:195], v[86:89]
	v_mfma_f32_16x16x32_bf16 v[78:81], v[154:157], v[200:203], v[78:81]
	v_mfma_f32_16x16x32_bf16 v[70:73], v[166:169], v[200:203], v[70:73]
	v_mfma_f32_16x16x32_bf16 v[122:125], v[204:207], v[170:173], v[122:125]
	v_mfma_f32_16x16x32_bf16 v[114:117], v[212:215], v[170:173], v[114:117]
	v_mfma_f32_16x16x32_bf16 v[106:109], v[204:207], v[180:183], v[106:109]
	v_mfma_f32_16x16x32_bf16 v[98:101], v[212:215], v[180:183], v[98:101]
	v_mfma_f32_16x16x32_bf16 v[90:93], v[204:207], v[188:191], v[90:93]
	v_mfma_f32_16x16x32_bf16 v[82:85], v[212:215], v[188:191], v[82:85]
	v_mfma_f32_16x16x32_bf16 v[74:77], v[204:207], v[196:199], v[74:77]
	v_mfma_f32_16x16x32_bf16 v[66:69], v[212:215], v[196:199], v[66:69]
	v_mfma_f32_16x16x32_bf16 v[122:125], v[208:211], v[174:177], v[122:125]
	v_mfma_f32_16x16x32_bf16 v[114:117], v[216:219], v[174:177], v[114:117]
	v_mfma_f32_16x16x32_bf16 v[106:109], v[208:211], v[184:187], v[106:109]
	v_mfma_f32_16x16x32_bf16 v[98:101], v[216:219], v[184:187], v[98:101]
	v_mfma_f32_16x16x32_bf16 v[90:93], v[208:211], v[192:195], v[90:93]
	v_mfma_f32_16x16x32_bf16 v[82:85], v[216:219], v[192:195], v[82:85]
	v_mfma_f32_16x16x32_bf16 v[74:77], v[208:211], v[200:203], v[74:77]
	v_mfma_f32_16x16x32_bf16 v[66:69], v[216:219], v[200:203], v[66:69]
	s_setprio 0
	s_barrier
; DI float sigmoidf_(float v) { return __builtin_amdgcn_rcpf(1.f + __expf(-v)); }
; #define EPI_SCHED __builtin_amdgcn_sched_barrier(0)
; DI void gemm_gateup(const Params& p, int bid, int nb, int tid) {
;     ...
;     _Pragma("unroll") for (int ai = 0; ai < 2; ++ai) _Pragma("unroll") for (int m = 0; m < 4; ++m) _Pragma("unroll") for (int n = 0; n < 2; ++n) {
;       const int col = pn * 128 + wc * 32 + n * 16 + fq * 4;
;       const int row = brow + ai * HALF + wr * 64 + m * 16 + fr;
;       const f32x4 g = acc[ai][0][m][n], uu = acc[ai][1][m][n];
;       uint2 w;
;       w.x = pk2(g[0] * sigmoidf_(g[0]) * uu[0], g[1] * sigmoidf_(g[1]) * uu[1]);
;       w.y = pk2(g[2] * sigmoidf_(g[2]) * uu[2], g[3] * sigmoidf_(g[3]) * uu[3]);
;       *reinterpret_cast<uint2*>(C + (size_t)row * DFF + col) = w;
;       EPI_SCHED;
;     }
	s_or_b32 s13, s15, 64
	s_or_b32 s12, s13, s12
	s_lshl_b32 s12, s12, 1
	v_readfirstlane_b32 s14, v139
	v_add_u32_e32 v149, s12, v130
	s_mov_b32 m0, s14
	s_nop 0
	global_load_lds_dwordx4 v149, s[82:83]
	v_add_u32_e32 v149, s12, v131
	v_readfirstlane_b32 s12, v140
	s_mov_b32 m0, s12
	s_nop 0
	global_load_lds_dwordx4 v149, s[82:83]
	s_or_b32 s12, s13, s16
	s_lshl_b32 s12, s12, 1
	v_readfirstlane_b32 s14, v141
	v_add_u32_e32 v149, s12, v130
	s_mov_b32 m0, s14
	ds_read_b128 v[170:173], v145 offset:49152
	ds_read_b128 v[174:177], v145 offset:50176
	ds_read_b128 v[180:183], v145 offset:51200
	ds_read_b128 v[184:187], v145 offset:52224
	ds_read_b128 v[188:191], v145 offset:53248
	ds_read_b128 v[192:195], v145 offset:54272
	ds_read_b128 v[196:199], v145 offset:55296
	ds_read_b128 v[200:203], v145 offset:56320
	global_load_lds_dwordx4 v149, s[80:81]
	v_add_u32_e32 v149, s12, v131
	v_readfirstlane_b32 s12, v142
	s_mov_b32 m0, s12
	s_nop 0
	global_load_lds_dwordx4 v149, s[80:81]
	s_or_b32 s12, s17, s13
	s_lshl_b32 s12, s12, 1
	v_readfirstlane_b32 s13, v143
	v_add_u32_e32 v149, s12, v130
	s_mov_b32 m0, s13
	s_nop 0
	global_load_lds_dwordx4 v149, s[82:83]
	v_add_u32_e32 v149, s12, v131
	v_readfirstlane_b32 s12, v144
	s_mov_b32 m0, s12
	s_nop 0
	global_load_lds_dwordx4 v149, s[82:83]
	s_waitcnt vmcnt(8)
	s_waitcnt lgkmcnt(0)
	s_barrier
	s_setprio 1
	v_mfma_f32_16x16x32_bf16 v[62:65], v[150:153], v[170:173], v[62:65]
	v_mfma_f32_16x16x32_bf16 v[54:57], v[158:161], v[170:173], v[54:57]
	v_mfma_f32_16x16x32_bf16 v[46:49], v[150:153], v[180:183], v[46:49]
	v_mfma_f32_16x16x32_bf16 v[38:41], v[158:161], v[180:183], v[38:41]
	v_mfma_f32_16x16x32_bf16 v[30:33], v[150:153], v[188:191], v[30:33]
	v_mfma_f32_16x16x32_bf16 v[22:25], v[158:161], v[188:191], v[22:25]
	v_mfma_f32_16x16x32_bf16 v[14:17], v[150:153], v[196:199], v[14:17]
	v_mfma_f32_16x16x32_bf16 v[6:9], v[158:161], v[196:199], v[6:9]
	v_mfma_f32_16x16x32_bf16 v[62:65], v[154:157], v[174:177], v[62:65]
	v_mfma_f32_16x16x32_bf16 v[54:57], v[166:169], v[174:177], v[54:57]
	v_mfma_f32_16x16x32_bf16 v[46:49], v[154:157], v[184:187], v[46:49]
	v_mfma_f32_16x16x32_bf16 v[38:41], v[166:169], v[184:187], v[38:41]
	v_mfma_f32_16x16x32_bf16 v[30:33], v[154:157], v[192:195], v[30:33]
	v_mfma_f32_16x16x32_bf16 v[22:25], v[166:169], v[192:195], v[22:25]
	v_mfma_f32_16x16x32_bf16 v[14:17], v[154:157], v[200:203], v[14:17]
	v_mfma_f32_16x16x32_bf16 v[6:9], v[166:169], v[200:203], v[6:9]
	v_mfma_f32_16x16x32_bf16 v[58:61], v[204:207], v[170:173], v[58:61]
	v_mfma_f32_16x16x32_bf16 v[50:53], v[212:215], v[170:173], v[50:53]
	v_mfma_f32_16x16x32_bf16 v[42:45], v[204:207], v[180:183], v[42:45]
	v_mfma_f32_16x16x32_bf16 v[34:37], v[212:215], v[180:183], v[34:37]
	v_mfma_f32_16x16x32_bf16 v[26:29], v[204:207], v[188:191], v[26:29]
	v_mfma_f32_16x16x32_bf16 v[18:21], v[212:215], v[188:191], v[18:21]
	v_mfma_f32_16x16x32_bf16 v[10:13], v[204:207], v[196:199], v[10:13]
	v_mfma_f32_16x16x32_bf16 v[2:5], v[212:215], v[196:199], v[2:5]
	v_mfma_f32_16x16x32_bf16 v[58:61], v[208:211], v[174:177], v[58:61]
	v_mfma_f32_16x16x32_bf16 v[50:53], v[216:219], v[174:177], v[50:53]
	v_mfma_f32_16x16x32_bf16 v[42:45], v[208:211], v[184:187], v[42:45]
	v_mfma_f32_16x16x32_bf16 v[34:37], v[216:219], v[184:187], v[34:37]
	v_mfma_f32_16x16x32_bf16 v[26:29], v[208:211], v[192:195], v[26:29]
	v_mfma_f32_16x16x32_bf16 v[18:21], v[216:219], v[192:195], v[18:21]
	v_mfma_f32_16x16x32_bf16 v[10:13], v[208:211], v[200:203], v[10:13]
	v_mfma_f32_16x16x32_bf16 v[2:5], v[216:219], v[200:203], v[2:5]
	s_setprio 0
	s_add_i32 s10, s10, 2
	s_cmp_gt_u32 s11, 29
	v_add_u32_e32 v148, 0x100, v148
	s_barrier
	s_cbranch_scc0 .LBB0_46
	v_mov_b32_e32 v148, v239
	s_lshl_b32 s7, s7, 7
	v_lshrrev_b32_e32 v149, 1, v148
	v_lshrrev_b32_e32 v150, 2, v148
	v_and_b32_e32 v149, 0x60, v149
	v_and_b32_e32 v150, 12, v150
	v_or3_b32 v150, v149, s7, v150
	v_ashrrev_i32_e32 v149, 2, v148
	v_and_b32_e32 v149, 0xffffffc0, v149
	v_and_or_b32 v148, v148, 15, s8
	v_add_u32_e32 v148, v148, v149
	v_mul_f32_e32 v149, 0xbfb8aa3b, v126
	v_exp_f32_e32 v149, v149
	s_movk_i32 s7, 0x2c00
	v_ashrrev_i32_e32 v151, 31, v150
	v_add_f32_e32 v149, 1.0, v149
	v_rcp_f32_e32 v152, v149
	v_mul_f32_e32 v149, 0xbfb8aa3b, v127
	v_exp_f32_e32 v149, v149
	s_nop 0
	v_add_f32_e32 v149, 1.0, v149
	v_rcp_f32_e32 v153, v149
	s_nop 0
	v_pk_mul_f32 v[126:127], v[126:127], v[152:153]
	s_nop 0
	v_pk_mul_f32 v[122:123], v[126:127], v[122:123]
	s_nop 0
	v_cvt_pk_bf16_f32 v126, v122, v123
	v_mul_f32_e32 v122, 0xbfb8aa3b, v128
	v_mul_f32_e32 v123, 0xbfb8aa3b, v129
	v_exp_f32_e32 v122, v122
	v_exp_f32_e32 v123, v123
	v_add_f32_e32 v122, 1.0, v122
	v_add_f32_e32 v123, 1.0, v123
	v_rcp_f32_e32 v122, v122
	v_rcp_f32_e32 v123, v123
	s_nop 0
	v_pk_mul_f32 v[122:123], v[128:129], v[122:123]
	s_nop 0
	v_pk_mul_f32 v[122:123], v[122:123], v[124:125]
	v_lshlrev_b64 v[124:125], 1, v[150:151]
	v_cvt_pk_bf16_f32 v127, v122, v123
	v_mov_b64_e32 v[122:123], s[76:77]
	v_mad_i64_i32 v[128:129], s[8:9], v148, s7, v[122:123]
	v_lshl_add_u64 v[128:129], v[128:129], 0, v[124:125]
	global_store_dwordx2 v[128:129], v[126:127], off
	v_mul_f32_e32 v126, 0xbfb8aa3b, v118
	v_mul_f32_e32 v127, 0xbfb8aa3b, v119
	v_exp_f32_e32 v126, v126
	v_exp_f32_e32 v127, v127
	v_add_f32_e32 v126, 1.0, v126
	v_add_f32_e32 v127, 1.0, v127
	v_rcp_f32_e32 v126, v126
	v_rcp_f32_e32 v127, v127
	s_nop 0
	v_pk_mul_f32 v[118:119], v[118:119], v[126:127]
	s_nop 0
	v_pk_mul_f32 v[114:115], v[118:119], v[114:115]
	s_nop 0
	v_cvt_pk_bf16_f32 v114, v114, v115
	v_mul_f32_e32 v115, 0xbfb8aa3b, v120
	v_exp_f32_e32 v115, v115
	s_nop 0
	v_add_f32_e32 v115, 1.0, v115
	v_rcp_f32_e32 v118, v115
; DI float sigmoidf_(float v) { return __builtin_amdgcn_rcpf(1.f + __expf(-v)); }
; #define EPI_SCHED __builtin_amdgcn_sched_barrier(0)
; DI void gemm_gateup(const Params& p, int bid, int nb, int tid) {
;     ...
;     _Pragma("unroll") for (int ai = 0; ai < 2; ++ai) _Pragma("unroll") for (int m = 0; m < 4; ++m) _Pragma("unroll") for (int n = 0; n < 2; ++n) {
;       const int col = pn * 128 + wc * 32 + n * 16 + fq * 4;
;       const int row = brow + ai * HALF + wr * 64 + m * 16 + fr;
;       const f32x4 g = acc[ai][0][m][n], uu = acc[ai][1][m][n];
;       uint2 w;
;       w.x = pk2(g[0] * sigmoidf_(g[0]) * uu[0], g[1] * sigmoidf_(g[1]) * uu[1]);
;       w.y = pk2(g[2] * sigmoidf_(g[2]) * uu[2], g[3] * sigmoidf_(g[3]) * uu[3]);
;       *reinterpret_cast<uint2*>(C + (size_t)row * DFF + col) = w;
;       EPI_SCHED;
;     }
	v_mul_f32_e32 v115, 0xbfb8aa3b, v121
	v_exp_f32_e32 v115, v115
	s_nop 0
	v_add_f32_e32 v115, 1.0, v115
	v_rcp_f32_e32 v119, v115
	s_nop 0
	v_pk_mul_f32 v[118:119], v[120:121], v[118:119]
	s_nop 0
	v_pk_mul_f32 v[116:117], v[118:119], v[116:117]
	s_nop 0
	v_cvt_pk_bf16_f32 v115, v116, v117
	global_store_dwordx2 v[128:129], v[114:115], off offset:32
	v_mul_f32_e32 v114, 0xbfb8aa3b, v110
	v_mul_f32_e32 v115, 0xbfb8aa3b, v111
	v_exp_f32_e32 v114, v114
	v_exp_f32_e32 v115, v115
	v_or_b32_e32 v116, 16, v148
	v_add_f32_e32 v114, 1.0, v114
	v_add_f32_e32 v115, 1.0, v115
	v_rcp_f32_e32 v114, v114
	v_rcp_f32_e32 v115, v115
	s_nop 0
	v_pk_mul_f32 v[110:111], v[110:111], v[114:115]
	s_nop 0
	v_pk_mul_f32 v[106:107], v[110:111], v[106:107]
	s_nop 0
	v_cvt_pk_bf16_f32 v106, v106, v107
	v_mul_f32_e32 v107, 0xbfb8aa3b, v112
	v_exp_f32_e32 v107, v107
	s_nop 0
	v_add_f32_e32 v107, 1.0, v107
	v_rcp_f32_e32 v110, v107
	v_mul_f32_e32 v107, 0xbfb8aa3b, v113
	v_exp_f32_e32 v107, v107
	s_nop 0
	v_add_f32_e32 v107, 1.0, v107
	v_rcp_f32_e32 v111, v107
	s_nop 0
	v_pk_mul_f32 v[110:111], v[112:113], v[110:111]
	s_nop 0
	v_pk_mul_f32 v[108:109], v[110:111], v[108:109]
	s_nop 0
	v_cvt_pk_bf16_f32 v107, v108, v109
	v_mad_i64_i32 v[108:109], s[8:9], v116, s7, v[122:123]
	v_lshl_add_u64 v[108:109], v[108:109], 0, v[124:125]
	global_store_dwordx2 v[108:109], v[106:107], off
	v_mul_f32_e32 v106, 0xbfb8aa3b, v102
	v_mul_f32_e32 v107, 0xbfb8aa3b, v103
	v_exp_f32_e32 v106, v106
	v_exp_f32_e32 v107, v107
	v_add_f32_e32 v106, 1.0, v106
	v_add_f32_e32 v107, 1.0, v107
	v_rcp_f32_e32 v106, v106
	v_rcp_f32_e32 v107, v107
	s_nop 0
	v_pk_mul_f32 v[102:103], v[102:103], v[106:107]
	s_nop 0
	v_pk_mul_f32 v[98:99], v[102:103], v[98:99]
	s_nop 0
	v_cvt_pk_bf16_f32 v98, v98, v99
	v_mul_f32_e32 v99, 0xbfb8aa3b, v104
	v_exp_f32_e32 v99, v99
	s_nop 0
	v_add_f32_e32 v99, 1.0, v99
	v_rcp_f32_e32 v102, v99
	v_mul_f32_e32 v99, 0xbfb8aa3b, v105
	v_exp_f32_e32 v99, v99
	s_nop 0
	v_add_f32_e32 v99, 1.0, v99
	v_rcp_f32_e32 v103, v99
	s_nop 0
	v_pk_mul_f32 v[102:103], v[104:105], v[102:103]
	s_nop 0
	v_pk_mul_f32 v[100:101], v[102:103], v[100:101]
	s_nop 0
	v_cvt_pk_bf16_f32 v99, v100, v101
	global_store_dwordx2 v[108:109], v[98:99], off offset:32
	v_mul_f32_e32 v98, 0xbfb8aa3b, v94
	v_mul_f32_e32 v99, 0xbfb8aa3b, v95
	v_exp_f32_e32 v98, v98
	v_exp_f32_e32 v99, v99
	v_or_b32_e32 v100, 32, v148
	v_add_f32_e32 v98, 1.0, v98
	v_add_f32_e32 v99, 1.0, v99
	v_rcp_f32_e32 v98, v98
	v_rcp_f32_e32 v99, v99
	s_nop 0
	v_pk_mul_f32 v[94:95], v[94:95], v[98:99]
	s_nop 0
	v_pk_mul_f32 v[90:91], v[94:95], v[90:91]
	s_nop 0
	v_cvt_pk_bf16_f32 v90, v90, v91
	v_mul_f32_e32 v91, 0xbfb8aa3b, v96
	v_exp_f32_e32 v91, v91
	s_nop 0
	v_add_f32_e32 v91, 1.0, v91
	v_rcp_f32_e32 v94, v91
	v_mul_f32_e32 v91, 0xbfb8aa3b, v97
	v_exp_f32_e32 v91, v91
	s_nop 0
	v_add_f32_e32 v91, 1.0, v91
	v_rcp_f32_e32 v95, v91
	s_nop 0
	v_pk_mul_f32 v[94:95], v[96:97], v[94:95]
	s_nop 0
	v_pk_mul_f32 v[92:93], v[94:95], v[92:93]
	s_nop 0
	v_cvt_pk_bf16_f32 v91, v92, v93
	v_mad_i64_i32 v[92:93], s[8:9], v100, s7, v[122:123]
	v_lshl_add_u64 v[92:93], v[92:93], 0, v[124:125]
	global_store_dwordx2 v[92:93], v[90:91], off
	v_mul_f32_e32 v90, 0xbfb8aa3b, v86
	v_mul_f32_e32 v91, 0xbfb8aa3b, v87
	v_exp_f32_e32 v90, v90
	v_exp_f32_e32 v91, v91
	v_add_f32_e32 v90, 1.0, v90
	v_add_f32_e32 v91, 1.0, v91
	v_rcp_f32_e32 v90, v90
	v_rcp_f32_e32 v91, v91
	s_nop 0
	v_pk_mul_f32 v[86:87], v[86:87], v[90:91]
	s_nop 0
	v_pk_mul_f32 v[82:83], v[86:87], v[82:83]
	s_nop 0
	v_cvt_pk_bf16_f32 v82, v82, v83
	v_mul_f32_e32 v83, 0xbfb8aa3b, v88
	v_exp_f32_e32 v83, v83
	s_nop 0
	v_add_f32_e32 v83, 1.0, v83
	v_rcp_f32_e32 v86, v83
	v_mul_f32_e32 v83, 0xbfb8aa3b, v89
	v_exp_f32_e32 v83, v83
	s_nop 0
	v_add_f32_e32 v83, 1.0, v83
	v_rcp_f32_e32 v87, v83
	s_nop 0
	v_pk_mul_f32 v[86:87], v[88:89], v[86:87]
	s_nop 0
	v_pk_mul_f32 v[84:85], v[86:87], v[84:85]
	s_nop 0
	v_cvt_pk_bf16_f32 v83, v84, v85
	global_store_dwordx2 v[92:93], v[82:83], off offset:32
	v_mul_f32_e32 v82, 0xbfb8aa3b, v78
	v_mul_f32_e32 v83, 0xbfb8aa3b, v79
	v_exp_f32_e32 v82, v82
	v_exp_f32_e32 v83, v83
	v_or_b32_e32 v84, 48, v148
	v_add_f32_e32 v82, 1.0, v82
	v_add_f32_e32 v83, 1.0, v83
	v_rcp_f32_e32 v82, v82
	v_rcp_f32_e32 v83, v83
	s_nop 0
	v_pk_mul_f32 v[78:79], v[78:79], v[82:83]
	s_nop 0
	v_pk_mul_f32 v[74:75], v[78:79], v[74:75]
	s_nop 0
	v_cvt_pk_bf16_f32 v74, v74, v75
	v_mul_f32_e32 v75, 0xbfb8aa3b, v80
	v_exp_f32_e32 v75, v75
	s_nop 0
	v_add_f32_e32 v75, 1.0, v75
	v_rcp_f32_e32 v78, v75
	v_mul_f32_e32 v75, 0xbfb8aa3b, v81
	v_exp_f32_e32 v75, v75
	s_nop 0
	v_add_f32_e32 v75, 1.0, v75
	v_rcp_f32_e32 v79, v75
	s_nop 0
	v_pk_mul_f32 v[78:79], v[80:81], v[78:79]
	s_nop 0
	v_pk_mul_f32 v[76:77], v[78:79], v[76:77]
	s_nop 0
	v_cvt_pk_bf16_f32 v75, v76, v77
	v_mad_i64_i32 v[76:77], s[8:9], v84, s7, v[122:123]
	v_lshl_add_u64 v[76:77], v[76:77], 0, v[124:125]
	global_store_dwordx2 v[76:77], v[74:75], off
	v_mul_f32_e32 v74, 0xbfb8aa3b, v70
	v_mul_f32_e32 v75, 0xbfb8aa3b, v71
	v_exp_f32_e32 v74, v74
	v_exp_f32_e32 v75, v75
	v_add_f32_e32 v74, 1.0, v74
	v_add_f32_e32 v75, 1.0, v75
	v_rcp_f32_e32 v74, v74
	v_rcp_f32_e32 v75, v75
	s_nop 0
	v_pk_mul_f32 v[70:71], v[70:71], v[74:75]
	s_nop 0
	v_pk_mul_f32 v[66:67], v[70:71], v[66:67]
	s_nop 0
	v_cvt_pk_bf16_f32 v66, v66, v67
	v_mul_f32_e32 v67, 0xbfb8aa3b, v72
	v_exp_f32_e32 v67, v67
	s_nop 0
	v_add_f32_e32 v67, 1.0, v67
	v_rcp_f32_e32 v70, v67
	v_mul_f32_e32 v67, 0xbfb8aa3b, v73
	v_exp_f32_e32 v67, v67
	s_nop 0
	v_add_f32_e32 v67, 1.0, v67
	v_rcp_f32_e32 v71, v67
	s_nop 0
	v_pk_mul_f32 v[70:71], v[72:73], v[70:71]
	s_nop 0
	v_pk_mul_f32 v[68:69], v[70:71], v[68:69]
; DI float sigmoidf_(float v) { return __builtin_amdgcn_rcpf(1.f + __expf(-v)); }
; #define EPI_SCHED __builtin_amdgcn_sched_barrier(0)
; DI void gemm_gateup(const Params& p, int bid, int nb, int tid) {
;     ...
;     _Pragma("unroll") for (int ai = 0; ai < 2; ++ai) _Pragma("unroll") for (int m = 0; m < 4; ++m) _Pragma("unroll") for (int n = 0; n < 2; ++n) {
;       const int col = pn * 128 + wc * 32 + n * 16 + fq * 4;
;       const int row = brow + ai * HALF + wr * 64 + m * 16 + fr;
;       const f32x4 g = acc[ai][0][m][n], uu = acc[ai][1][m][n];
;       uint2 w;
;       w.x = pk2(g[0] * sigmoidf_(g[0]) * uu[0], g[1] * sigmoidf_(g[1]) * uu[1]);
;       w.y = pk2(g[2] * sigmoidf_(g[2]) * uu[2], g[3] * sigmoidf_(g[3]) * uu[3]);
;       *reinterpret_cast<uint2*>(C + (size_t)row * DFF + col) = w;
;       EPI_SCHED;
;     }
	s_nop 0
	v_cvt_pk_bf16_f32 v67, v68, v69
	global_store_dwordx2 v[76:77], v[66:67], off offset:32
	v_mul_f32_e32 v66, 0xbfb8aa3b, v62
	v_mul_f32_e32 v67, 0xbfb8aa3b, v63
	v_exp_f32_e32 v66, v66
	v_exp_f32_e32 v67, v67
	v_add_u32_e32 v68, 0x80, v148
	v_add_f32_e32 v66, 1.0, v66
	v_add_f32_e32 v67, 1.0, v67
	v_rcp_f32_e32 v66, v66
	v_rcp_f32_e32 v67, v67
	s_nop 0
	v_pk_mul_f32 v[62:63], v[62:63], v[66:67]
	s_nop 0
	v_pk_mul_f32 v[58:59], v[62:63], v[58:59]
	s_nop 0
	v_cvt_pk_bf16_f32 v58, v58, v59
	v_mul_f32_e32 v59, 0xbfb8aa3b, v64
	v_exp_f32_e32 v59, v59
	s_nop 0
	v_add_f32_e32 v59, 1.0, v59
	v_rcp_f32_e32 v62, v59
	v_mul_f32_e32 v59, 0xbfb8aa3b, v65
	v_exp_f32_e32 v59, v59
	s_nop 0
	v_add_f32_e32 v59, 1.0, v59
	v_rcp_f32_e32 v63, v59
	s_nop 0
	v_pk_mul_f32 v[62:63], v[64:65], v[62:63]
	s_nop 0
	v_pk_mul_f32 v[60:61], v[62:63], v[60:61]
	s_nop 0
	v_cvt_pk_bf16_f32 v59, v60, v61
	v_mad_i64_i32 v[60:61], s[8:9], v68, s7, v[122:123]
	v_lshl_add_u64 v[60:61], v[60:61], 0, v[124:125]
	global_store_dwordx2 v[60:61], v[58:59], off
	v_mul_f32_e32 v58, 0xbfb8aa3b, v54
	v_mul_f32_e32 v59, 0xbfb8aa3b, v55
	v_exp_f32_e32 v58, v58
	v_exp_f32_e32 v59, v59
	v_add_f32_e32 v58, 1.0, v58
	v_add_f32_e32 v59, 1.0, v59
	v_rcp_f32_e32 v58, v58
	v_rcp_f32_e32 v59, v59
	s_nop 0
	v_pk_mul_f32 v[54:55], v[54:55], v[58:59]
	s_nop 0
	v_pk_mul_f32 v[50:51], v[54:55], v[50:51]
	s_nop 0
	v_cvt_pk_bf16_f32 v50, v50, v51
	v_mul_f32_e32 v51, 0xbfb8aa3b, v56
	v_exp_f32_e32 v51, v51
	s_nop 0
	v_add_f32_e32 v51, 1.0, v51
	v_rcp_f32_e32 v54, v51
	v_mul_f32_e32 v51, 0xbfb8aa3b, v57
	v_exp_f32_e32 v51, v51
	s_nop 0
	v_add_f32_e32 v51, 1.0, v51
	v_rcp_f32_e32 v55, v51
	s_nop 0
	v_pk_mul_f32 v[54:55], v[56:57], v[54:55]
	s_nop 0
	v_pk_mul_f32 v[52:53], v[54:55], v[52:53]
	s_nop 0
	v_cvt_pk_bf16_f32 v51, v52, v53
	global_store_dwordx2 v[60:61], v[50:51], off offset:32
	v_mul_f32_e32 v50, 0xbfb8aa3b, v46
	v_mul_f32_e32 v51, 0xbfb8aa3b, v47
	v_exp_f32_e32 v50, v50
	v_exp_f32_e32 v51, v51
	v_add_u32_e32 v52, 0x90, v148
	v_add_f32_e32 v50, 1.0, v50
	v_add_f32_e32 v51, 1.0, v51
	v_rcp_f32_e32 v50, v50
	v_rcp_f32_e32 v51, v51
	s_nop 0
	v_pk_mul_f32 v[46:47], v[46:47], v[50:51]
	s_nop 0
	v_pk_mul_f32 v[42:43], v[46:47], v[42:43]
	s_nop 0
	v_cvt_pk_bf16_f32 v42, v42, v43
	v_mul_f32_e32 v43, 0xbfb8aa3b, v48
	v_exp_f32_e32 v43, v43
	s_nop 0
	v_add_f32_e32 v43, 1.0, v43
	v_rcp_f32_e32 v46, v43
	v_mul_f32_e32 v43, 0xbfb8aa3b, v49
	v_exp_f32_e32 v43, v43
	s_nop 0
	v_add_f32_e32 v43, 1.0, v43
	v_rcp_f32_e32 v47, v43
	s_nop 0
	v_pk_mul_f32 v[46:47], v[48:49], v[46:47]
	s_nop 0
	v_pk_mul_f32 v[44:45], v[46:47], v[44:45]
	s_nop 0
	v_cvt_pk_bf16_f32 v43, v44, v45
	v_mad_i64_i32 v[44:45], s[8:9], v52, s7, v[122:123]
	v_lshl_add_u64 v[44:45], v[44:45], 0, v[124:125]
	global_store_dwordx2 v[44:45], v[42:43], off
	v_mul_f32_e32 v42, 0xbfb8aa3b, v38
	v_mul_f32_e32 v43, 0xbfb8aa3b, v39
	v_exp_f32_e32 v42, v42
	v_exp_f32_e32 v43, v43
	v_add_f32_e32 v42, 1.0, v42
	v_add_f32_e32 v43, 1.0, v43
	v_rcp_f32_e32 v42, v42
	v_rcp_f32_e32 v43, v43
	s_nop 0
	v_pk_mul_f32 v[38:39], v[38:39], v[42:43]
	s_nop 0
	v_pk_mul_f32 v[34:35], v[38:39], v[34:35]
	s_nop 0
	v_cvt_pk_bf16_f32 v34, v34, v35
	v_mul_f32_e32 v35, 0xbfb8aa3b, v40
	v_exp_f32_e32 v35, v35
	s_nop 0
	v_add_f32_e32 v35, 1.0, v35
	v_rcp_f32_e32 v38, v35
	v_mul_f32_e32 v35, 0xbfb8aa3b, v41
	v_exp_f32_e32 v35, v35
	s_nop 0
	v_add_f32_e32 v35, 1.0, v35
	v_rcp_f32_e32 v39, v35
	s_nop 0
	v_pk_mul_f32 v[38:39], v[40:41], v[38:39]
	s_nop 0
	v_pk_mul_f32 v[36:37], v[38:39], v[36:37]
	s_nop 0
	v_cvt_pk_bf16_f32 v35, v36, v37
	global_store_dwordx2 v[44:45], v[34:35], off offset:32
	v_mul_f32_e32 v34, 0xbfb8aa3b, v30
; DI float sigmoidf_(float v) { return __builtin_amdgcn_rcpf(1.f + __expf(-v)); }
; #define WAIT_V(n) asm volatile("s_waitcnt vmcnt(" #n ")" ::: "memory")
; #define BAR __builtin_amdgcn_s_barrier()
; #define EPI_SCHED __builtin_amdgcn_sched_barrier(0)
; template <class EPI>
; DI void gemm_stream(const u16* __restrict__ A, const u16* __restrict__ Bt, const int K, const int nM, const int nN,
;                     const int bid, const int nb, const int tid, EPI epi) {
;     ...
;     brow = brow2; bcol = bcol2; pm = pm2; pn = pn2;
;   }
;   WAIT_V(0);
;   if (wr == 0) BAR;
;   BAR;
; DI void gemm_gateup(const Params& p, int bid, int nb, int tid) {
;     ...
;     _Pragma("unroll") for (int ai = 0; ai < 2; ++ai) _Pragma("unroll") for (int m = 0; m < 4; ++m) _Pragma("unroll") for (int n = 0; n < 2; ++n) {
;       const int col = pn * 128 + wc * 32 + n * 16 + fq * 4;
;       const int row = brow + ai * HALF + wr * 64 + m * 16 + fr;
;       const f32x4 g = acc[ai][0][m][n], uu = acc[ai][1][m][n];
;       uint2 w;
;       w.x = pk2(g[0] * sigmoidf_(g[0]) * uu[0], g[1] * sigmoidf_(g[1]) * uu[1]);
;       w.y = pk2(g[2] * sigmoidf_(g[2]) * uu[2], g[3] * sigmoidf_(g[3]) * uu[3]);
;       *reinterpret_cast<uint2*>(C + (size_t)row * DFF + col) = w;
;       EPI_SCHED;
;     }
	v_mul_f32_e32 v35, 0xbfb8aa3b, v31
	v_exp_f32_e32 v34, v34
	v_exp_f32_e32 v35, v35
	v_add_u32_e32 v36, 0xa0, v148
	v_add_f32_e32 v34, 1.0, v34
	v_add_f32_e32 v35, 1.0, v35
	v_rcp_f32_e32 v34, v34
	v_rcp_f32_e32 v35, v35
	s_nop 0
	v_pk_mul_f32 v[30:31], v[30:31], v[34:35]
	s_nop 0
	v_pk_mul_f32 v[26:27], v[30:31], v[26:27]
	s_nop 0
	v_cvt_pk_bf16_f32 v26, v26, v27
	v_mul_f32_e32 v27, 0xbfb8aa3b, v32
	v_exp_f32_e32 v27, v27
	s_nop 0
	v_add_f32_e32 v27, 1.0, v27
	v_rcp_f32_e32 v30, v27
	v_mul_f32_e32 v27, 0xbfb8aa3b, v33
	v_exp_f32_e32 v27, v27
	s_nop 0
	v_add_f32_e32 v27, 1.0, v27
	v_rcp_f32_e32 v31, v27
	s_nop 0
	v_pk_mul_f32 v[30:31], v[32:33], v[30:31]
	s_nop 0
	v_pk_mul_f32 v[28:29], v[30:31], v[28:29]
	s_nop 0
	v_cvt_pk_bf16_f32 v27, v28, v29
	v_mad_i64_i32 v[28:29], s[8:9], v36, s7, v[122:123]
	v_lshl_add_u64 v[28:29], v[28:29], 0, v[124:125]
	global_store_dwordx2 v[28:29], v[26:27], off
	v_mul_f32_e32 v26, 0xbfb8aa3b, v22
	v_mul_f32_e32 v27, 0xbfb8aa3b, v23
	v_exp_f32_e32 v26, v26
	v_exp_f32_e32 v27, v27
	v_add_f32_e32 v26, 1.0, v26
	v_add_f32_e32 v27, 1.0, v27
	v_rcp_f32_e32 v26, v26
	v_rcp_f32_e32 v27, v27
	s_nop 0
	v_pk_mul_f32 v[22:23], v[22:23], v[26:27]
	s_nop 0
	v_pk_mul_f32 v[18:19], v[22:23], v[18:19]
	s_nop 0
	v_cvt_pk_bf16_f32 v18, v18, v19
	v_mul_f32_e32 v19, 0xbfb8aa3b, v24
	v_exp_f32_e32 v19, v19
	s_nop 0
	v_add_f32_e32 v19, 1.0, v19
	v_rcp_f32_e32 v22, v19
	v_mul_f32_e32 v19, 0xbfb8aa3b, v25
	v_exp_f32_e32 v19, v19
	s_nop 0
	v_add_f32_e32 v19, 1.0, v19
	v_rcp_f32_e32 v23, v19
	s_nop 0
	v_pk_mul_f32 v[22:23], v[24:25], v[22:23]
	s_nop 0
	v_pk_mul_f32 v[20:21], v[22:23], v[20:21]
	s_nop 0
	v_cvt_pk_bf16_f32 v19, v20, v21
	global_store_dwordx2 v[28:29], v[18:19], off offset:32
	v_mul_f32_e32 v18, 0xbfb8aa3b, v14
	v_mul_f32_e32 v19, 0xbfb8aa3b, v15
	v_exp_f32_e32 v18, v18
	v_exp_f32_e32 v19, v19
	v_add_u32_e32 v20, 0xb0, v148
	v_add_f32_e32 v18, 1.0, v18
	v_add_f32_e32 v19, 1.0, v19
	v_rcp_f32_e32 v18, v18
	v_rcp_f32_e32 v19, v19
	s_nop 0
	v_pk_mul_f32 v[14:15], v[14:15], v[18:19]
	s_nop 0
	v_pk_mul_f32 v[10:11], v[14:15], v[10:11]
	s_nop 0
	v_cvt_pk_bf16_f32 v10, v10, v11
	v_mul_f32_e32 v11, 0xbfb8aa3b, v16
	v_exp_f32_e32 v11, v11
	s_nop 0
	v_add_f32_e32 v11, 1.0, v11
	v_rcp_f32_e32 v14, v11
	v_mul_f32_e32 v11, 0xbfb8aa3b, v17
	v_exp_f32_e32 v11, v11
	s_nop 0
	v_add_f32_e32 v11, 1.0, v11
	v_rcp_f32_e32 v15, v11
	s_nop 0
	v_pk_mul_f32 v[14:15], v[16:17], v[14:15]
	s_nop 0
	v_pk_mul_f32 v[12:13], v[14:15], v[12:13]
	s_nop 0
	v_cvt_pk_bf16_f32 v11, v12, v13
	v_mad_i64_i32 v[12:13], s[8:9], v20, s7, v[122:123]
	v_lshl_add_u64 v[12:13], v[12:13], 0, v[124:125]
	global_store_dwordx2 v[12:13], v[10:11], off
	v_mul_f32_e32 v10, 0xbfb8aa3b, v6
	v_mul_f32_e32 v11, 0xbfb8aa3b, v7
	v_exp_f32_e32 v10, v10
	v_exp_f32_e32 v11, v11
	v_add_f32_e32 v10, 1.0, v10
	v_add_f32_e32 v11, 1.0, v11
	v_rcp_f32_e32 v10, v10
	v_rcp_f32_e32 v11, v11
	s_nop 0
	v_pk_mul_f32 v[6:7], v[6:7], v[10:11]
	s_nop 0
	v_pk_mul_f32 v[2:3], v[6:7], v[2:3]
	s_nop 0
	v_cvt_pk_bf16_f32 v2, v2, v3
	v_mul_f32_e32 v3, 0xbfb8aa3b, v8
	v_exp_f32_e32 v3, v3
	s_nop 0
	v_add_f32_e32 v3, 1.0, v3
	v_rcp_f32_e32 v6, v3
	v_mul_f32_e32 v3, 0xbfb8aa3b, v9
	v_exp_f32_e32 v3, v3
	s_nop 0
	v_add_f32_e32 v3, 1.0, v3
	v_rcp_f32_e32 v7, v3
	s_nop 0
	v_pk_mul_f32 v[6:7], v[8:9], v[6:7]
	s_nop 0
	v_pk_mul_f32 v[4:5], v[6:7], v[4:5]
	s_nop 0
	v_cvt_pk_bf16_f32 v3, v4, v5
	global_store_dwordx2 v[12:13], v[2:3], off offset:32
	s_and_b64 vcc, exec, s[0:1]
	s_mov_b32 s8, s5
	s_mov_b32 s9, s6
	s_mov_b32 s7, s4
	s_cbranch_vccz .LBB0_43
	s_waitcnt vmcnt(0)
	s_movk_i32 s0, 0x100
	v_cmp_gt_u32_e32 vcc, s0, v239
	s_and_saveexec_b64 s[0:1], vcc
	s_cbranch_execz .LBB0_50
	s_barrier

.LBB0_132:
	v_or_b32_e32 v131, 0x10000, v167
	v_add_u32_e32 v136, 0x10400, v167
	v_add_u32_e32 v140, 0x10800, v167
	v_add_u32_e32 v144, 0x10c00, v167
	s_add_i32 s11, s10, 2
	ds_read_b128 v[132:135], v131
	ds_read_b128 v[136:139], v136
	ds_read_b128 v[140:143], v140
	ds_read_b128 v[144:147], v144
	s_cmp_lt_u32 s10, 30
	s_cselect_b32 s12, s8, s5
	s_cselect_b32 s13, s7, s6
	s_cselect_b32 s14, s9, 0
	s_lshl_b32 s13, s13, 11
	s_lshl_b32 s12, s12, 11
	s_or_b32 s15, s14, 64
	s_add_i32 s17, s12, s14
	s_or_b32 s18, s13, 0x40000
	s_add_i32 s16, s13, s14
	s_add_i32 s13, s15, s13
	s_add_i32 s12, s15, s12
	s_lshl_b32 s17, s17, 1
	s_add_i32 s19, s18, s14
	s_add_i32 s18, s18, s15
	s_addk_i32 s9, 0x80
	s_lshl_b32 s16, s16, 1
	s_lshl_b32 s14, s13, 1
	s_lshl_b32 s13, s12, 1
	s_lshl_b32 s15, s19, 1
	s_add_i32 s19, s17, 0x80000
	s_lshl_b32 s12, s18, 1
	s_cmp_gt_u32 s10, 29
	v_add_u32_e32 v148, 0xc000, v0
	v_add_u32_e32 v131, 0xfffc0000, v130
	v_readfirstlane_b32 s10, v148
	s_mov_b32 m0, s10
	ds_read_b128 v[170:173], v166
	ds_read_b128 v[174:177], v166 offset:1024
	ds_read_b128 v[180:183], v166 offset:2048
	ds_read_b128 v[184:187], v166 offset:3072
	ds_read_b128 v[188:191], v166 offset:4096
	ds_read_b128 v[192:195], v166 offset:5120
	ds_read_b128 v[196:199], v166 offset:6144
	ds_read_b128 v[200:203], v166 offset:7168
	global_load_lds_dwordx4 v131, s[86:87]
	v_add_u32_e32 v131, 0xe000, v0
	s_nop 0
	v_readfirstlane_b32 s10, v131
	s_mov_b32 m0, s10
	s_nop 0
	global_load_lds_dwordx4 v130, s[86:87]
	v_or_b32_e32 v131, 0x14000, v167
	v_add_u32_e32 v148, 0x14400, v167
	ds_read_b128 v[204:207], v131
	ds_read_b128 v[208:211], v148
	v_add_u32_e32 v131, 0x14800, v167
	v_add_u32_e32 v148, 0x14c00, v167
	ds_read_b128 v[212:215], v131
	ds_read_b128 v[216:219], v148
	s_waitcnt vmcnt(8)
	s_waitcnt lgkmcnt(0)
	s_barrier
	s_setprio 1
	v_mfma_f32_16x16x32_bf16 v[98:101], v[132:135], v[170:173], v[98:101]
	v_mfma_f32_16x16x32_bf16 v[102:105], v[140:143], v[170:173], v[102:105]
	v_mfma_f32_16x16x32_bf16 v[126:129], v[132:135], v[180:183], v[126:129]
	v_mfma_f32_16x16x32_bf16 v[122:125], v[140:143], v[180:183], v[122:125]
	v_mfma_f32_16x16x32_bf16 v[118:121], v[132:135], v[188:191], v[118:121]
	v_mfma_f32_16x16x32_bf16 v[114:117], v[140:143], v[188:191], v[114:117]
	v_mfma_f32_16x16x32_bf16 v[110:113], v[132:135], v[196:199], v[110:113]
	v_mfma_f32_16x16x32_bf16 v[106:109], v[140:143], v[196:199], v[106:109]
	v_mfma_f32_16x16x32_bf16 v[98:101], v[136:139], v[174:177], v[98:101]
	v_mfma_f32_16x16x32_bf16 v[102:105], v[144:147], v[174:177], v[102:105]
	v_mfma_f32_16x16x32_bf16 v[126:129], v[136:139], v[184:187], v[126:129]
	v_mfma_f32_16x16x32_bf16 v[122:125], v[144:147], v[184:187], v[122:125]
	v_mfma_f32_16x16x32_bf16 v[118:121], v[136:139], v[192:195], v[118:121]
	v_mfma_f32_16x16x32_bf16 v[114:117], v[144:147], v[192:195], v[114:117]
	v_mfma_f32_16x16x32_bf16 v[110:113], v[136:139], v[200:203], v[110:113]
	v_mfma_f32_16x16x32_bf16 v[106:109], v[144:147], v[200:203], v[106:109]
	v_mfma_f32_16x16x32_bf16 v[66:69], v[204:207], v[170:173], v[66:69]
	v_mfma_f32_16x16x32_bf16 v[70:73], v[212:215], v[170:173], v[70:73]
	v_mfma_f32_16x16x32_bf16 v[74:77], v[204:207], v[180:183], v[74:77]
	v_mfma_f32_16x16x32_bf16 v[78:81], v[212:215], v[180:183], v[78:81]
	v_mfma_f32_16x16x32_bf16 v[82:85], v[204:207], v[188:191], v[82:85]
	v_mfma_f32_16x16x32_bf16 v[86:89], v[212:215], v[188:191], v[86:89]
	v_mfma_f32_16x16x32_bf16 v[90:93], v[204:207], v[196:199], v[90:93]
	v_mfma_f32_16x16x32_bf16 v[94:97], v[212:215], v[196:199], v[94:97]
	v_mfma_f32_16x16x32_bf16 v[66:69], v[208:211], v[174:177], v[66:69]
	v_mfma_f32_16x16x32_bf16 v[70:73], v[216:219], v[174:177], v[70:73]
	v_mfma_f32_16x16x32_bf16 v[74:77], v[208:211], v[184:187], v[74:77]
	v_mfma_f32_16x16x32_bf16 v[78:81], v[216:219], v[184:187], v[78:81]
	v_mfma_f32_16x16x32_bf16 v[82:85], v[208:211], v[192:195], v[82:85]
	v_mfma_f32_16x16x32_bf16 v[86:89], v[216:219], v[192:195], v[86:89]
	v_mfma_f32_16x16x32_bf16 v[90:93], v[208:211], v[200:203], v[90:93]
	v_mfma_f32_16x16x32_bf16 v[94:97], v[216:219], v[200:203], v[94:97]
	s_setprio 0
	s_barrier
	v_readfirstlane_b32 s10, v152
	v_add_u32_e32 v131, s16, v150
	s_mov_b32 m0, s10
	v_readfirstlane_b32 s10, v153
	global_load_lds_dwordx4 v131, s[88:89]
	v_add_u32_e32 v131, s16, v151
	s_mov_b32 m0, s10
	s_nop 0
	global_load_lds_dwordx4 v131, s[88:89]
	v_readfirstlane_b32 s10, v0
	v_add_u32_e32 v131, s17, v150
	s_mov_b32 m0, s10
	v_readfirstlane_b32 s10, v154
	ds_read_b128 v[170:173], v166 offset:16384
	ds_read_b128 v[174:177], v166 offset:17408
	ds_read_b128 v[180:183], v166 offset:18432
	ds_read_b128 v[184:187], v166 offset:19456
	ds_read_b128 v[188:191], v166 offset:20480
	ds_read_b128 v[192:195], v166 offset:21504
	ds_read_b128 v[196:199], v166 offset:22528
	ds_read_b128 v[200:203], v166 offset:23552
	global_load_lds_dwordx4 v131, s[86:87]
	v_add_u32_e32 v131, s17, v151
	s_mov_b32 m0, s10
	s_nop 0
	global_load_lds_dwordx4 v131, s[86:87]
	v_readfirstlane_b32 s10, v155
	v_add_u32_e32 v131, s15, v150
	s_mov_b32 m0, s10
	v_readfirstlane_b32 s10, v156
	global_load_lds_dwordx4 v131, s[88:89]
	v_add_u32_e32 v131, s15, v151
	s_mov_b32 m0, s10
	s_nop 0
	global_load_lds_dwordx4 v131, s[88:89]
	s_waitcnt vmcnt(8)
	s_waitcnt lgkmcnt(0)
	s_barrier
	s_setprio 1
	v_mfma_f32_16x16x32_bf16 v[34:37], v[132:135], v[170:173], v[34:37]
	v_mfma_f32_16x16x32_bf16 v[38:41], v[140:143], v[170:173], v[38:41]
	v_mfma_f32_16x16x32_bf16 v[42:45], v[132:135], v[180:183], v[42:45]
	v_mfma_f32_16x16x32_bf16 v[46:49], v[140:143], v[180:183], v[46:49]
	v_mfma_f32_16x16x32_bf16 v[50:53], v[132:135], v[188:191], v[50:53]
	v_mfma_f32_16x16x32_bf16 v[54:57], v[140:143], v[188:191], v[54:57]
	v_mfma_f32_16x16x32_bf16 v[58:61], v[132:135], v[196:199], v[58:61]
	v_mfma_f32_16x16x32_bf16 v[62:65], v[140:143], v[196:199], v[62:65]
	v_mfma_f32_16x16x32_bf16 v[34:37], v[136:139], v[174:177], v[34:37]
	v_mfma_f32_16x16x32_bf16 v[38:41], v[144:147], v[174:177], v[38:41]
	v_mfma_f32_16x16x32_bf16 v[42:45], v[136:139], v[184:187], v[42:45]
	v_mfma_f32_16x16x32_bf16 v[46:49], v[144:147], v[184:187], v[46:49]
	v_mfma_f32_16x16x32_bf16 v[50:53], v[136:139], v[192:195], v[50:53]
	v_mfma_f32_16x16x32_bf16 v[54:57], v[144:147], v[192:195], v[54:57]
	v_mfma_f32_16x16x32_bf16 v[58:61], v[136:139], v[200:203], v[58:61]
	v_mfma_f32_16x16x32_bf16 v[62:65], v[144:147], v[200:203], v[62:65]
	v_mfma_f32_16x16x32_bf16 v[2:5], v[204:207], v[170:173], v[2:5]
	v_mfma_f32_16x16x32_bf16 v[6:9], v[212:215], v[170:173], v[6:9]
	v_mfma_f32_16x16x32_bf16 v[10:13], v[204:207], v[180:183], v[10:13]
	v_mfma_f32_16x16x32_bf16 v[14:17], v[212:215], v[180:183], v[14:17]
	v_mfma_f32_16x16x32_bf16 v[18:21], v[204:207], v[188:191], v[18:21]
	v_mfma_f32_16x16x32_bf16 v[22:25], v[212:215], v[188:191], v[22:25]
	v_mfma_f32_16x16x32_bf16 v[26:29], v[204:207], v[196:199], v[26:29]
	v_mfma_f32_16x16x32_bf16 v[30:33], v[212:215], v[196:199], v[30:33]
	v_mfma_f32_16x16x32_bf16 v[2:5], v[208:211], v[174:177], v[2:5]
	v_mfma_f32_16x16x32_bf16 v[6:9], v[216:219], v[174:177], v[6:9]
	v_mfma_f32_16x16x32_bf16 v[10:13], v[208:211], v[184:187], v[10:13]
	v_mfma_f32_16x16x32_bf16 v[14:17], v[216:219], v[184:187], v[14:17]
	v_mfma_f32_16x16x32_bf16 v[18:21], v[208:211], v[192:195], v[18:21]
	v_mfma_f32_16x16x32_bf16 v[22:25], v[216:219], v[192:195], v[22:25]
	v_mfma_f32_16x16x32_bf16 v[26:29], v[208:211], v[200:203], v[26:29]
	v_mfma_f32_16x16x32_bf16 v[30:33], v[216:219], v[200:203], v[30:33]
	s_setprio 0
	s_barrier
	v_or_b32_e32 v131, 0x18000, v167
	v_add_u32_e32 v136, 0x18400, v167
	ds_read_b128 v[132:135], v131
	ds_read_b128 v[136:139], v136
	v_add_u32_e32 v131, 0x18800, v167
	v_add_u32_e32 v144, 0x18c00, v167
	ds_read_b128 v[140:143], v131
	ds_read_b128 v[144:147], v144
	v_readfirstlane_b32 s10, v157
	v_add_u32_e32 v131, s19, v150
	s_mov_b32 m0, s10
	v_readfirstlane_b32 s10, v158
	ds_read_b128 v[170:173], v166 offset:32768
	ds_read_b128 v[174:177], v166 offset:33792
	ds_read_b128 v[180:183], v166 offset:34816
	ds_read_b128 v[184:187], v166 offset:35840
	ds_read_b128 v[188:191], v166 offset:36864
	ds_read_b128 v[192:195], v166 offset:37888
	ds_read_b128 v[196:199], v166 offset:38912
	ds_read_b128 v[200:203], v166 offset:39936
	global_load_lds_dwordx4 v131, s[86:87]
	v_add_u32_e32 v131, s19, v151
	s_mov_b32 m0, s10
	s_nop 0
	global_load_lds_dwordx4 v131, s[86:87]
	v_or_b32_e32 v131, 0x1c000, v167
	v_add_u32_e32 v148, 0x1c400, v167
	ds_read_b128 v[204:207], v131
	ds_read_b128 v[208:211], v148
	v_add_u32_e32 v131, 0x1c800, v167
	v_add_u32_e32 v148, 0x1cc00, v167
	ds_read_b128 v[212:215], v131
	ds_read_b128 v[216:219], v148
	s_waitcnt vmcnt(8)
	s_waitcnt lgkmcnt(0)
	s_barrier
	s_setprio 1
	v_mfma_f32_16x16x32_bf16 v[98:101], v[132:135], v[170:173], v[98:101]
	v_mfma_f32_16x16x32_bf16 v[102:105], v[140:143], v[170:173], v[102:105]
	v_mfma_f32_16x16x32_bf16 v[126:129], v[132:135], v[180:183], v[126:129]
	v_mfma_f32_16x16x32_bf16 v[122:125], v[140:143], v[180:183], v[122:125]
	v_mfma_f32_16x16x32_bf16 v[118:121], v[132:135], v[188:191], v[118:121]
	v_mfma_f32_16x16x32_bf16 v[114:117], v[140:143], v[188:191], v[114:117]
	v_mfma_f32_16x16x32_bf16 v[110:113], v[132:135], v[196:199], v[110:113]
	v_mfma_f32_16x16x32_bf16 v[106:109], v[140:143], v[196:199], v[106:109]
	v_mfma_f32_16x16x32_bf16 v[98:101], v[136:139], v[174:177], v[98:101]
	v_mfma_f32_16x16x32_bf16 v[102:105], v[144:147], v[174:177], v[102:105]
	v_mfma_f32_16x16x32_bf16 v[126:129], v[136:139], v[184:187], v[126:129]
	v_mfma_f32_16x16x32_bf16 v[122:125], v[144:147], v[184:187], v[122:125]
	v_mfma_f32_16x16x32_bf16 v[118:121], v[136:139], v[192:195], v[118:121]
	v_mfma_f32_16x16x32_bf16 v[114:117], v[144:147], v[192:195], v[114:117]
	v_mfma_f32_16x16x32_bf16 v[110:113], v[136:139], v[200:203], v[110:113]
	v_mfma_f32_16x16x32_bf16 v[106:109], v[144:147], v[200:203], v[106:109]
	v_mfma_f32_16x16x32_bf16 v[66:69], v[204:207], v[170:173], v[66:69]
	v_mfma_f32_16x16x32_bf16 v[70:73], v[212:215], v[170:173], v[70:73]
	v_mfma_f32_16x16x32_bf16 v[74:77], v[204:207], v[180:183], v[74:77]
	v_mfma_f32_16x16x32_bf16 v[78:81], v[212:215], v[180:183], v[78:81]
	v_mfma_f32_16x16x32_bf16 v[82:85], v[204:207], v[188:191], v[82:85]
	v_mfma_f32_16x16x32_bf16 v[86:89], v[212:215], v[188:191], v[86:89]
	v_mfma_f32_16x16x32_bf16 v[90:93], v[204:207], v[196:199], v[90:93]
	v_mfma_f32_16x16x32_bf16 v[94:97], v[212:215], v[196:199], v[94:97]
	v_mfma_f32_16x16x32_bf16 v[66:69], v[208:211], v[174:177], v[66:69]
	v_mfma_f32_16x16x32_bf16 v[70:73], v[216:219], v[174:177], v[70:73]
	v_mfma_f32_16x16x32_bf16 v[74:77], v[208:211], v[184:187], v[74:77]
	v_mfma_f32_16x16x32_bf16 v[78:81], v[216:219], v[184:187], v[78:81]
	v_mfma_f32_16x16x32_bf16 v[82:85], v[208:211], v[192:195], v[82:85]
	v_mfma_f32_16x16x32_bf16 v[86:89], v[216:219], v[192:195], v[86:89]
	v_mfma_f32_16x16x32_bf16 v[90:93], v[208:211], v[200:203], v[90:93]
	v_mfma_f32_16x16x32_bf16 v[94:97], v[216:219], v[200:203], v[94:97]
	s_setprio 0
	s_barrier
; #define EPI_SCHED __builtin_amdgcn_sched_barrier(0)
; DI void gemm_resid(const u16* A, const u16* Bt, int K, const float* xin, float* xout, int bid, int nb, int tid) {
;     ...
; #pragma unroll
;     for (int ai = 0; ai < 2; ++ai)
; #pragma unroll
;       for (int bj = 0; bj < 2; ++bj) {
;         float4 xi[4][2];
; #pragma unroll
;         for (int m = 0; m < 4; ++m)
; #pragma unroll
;           for (int n = 0; n < 2; ++n) xi[m][n] = *reinterpret_cast<const float4*>(xin + (size_t)ACC_ROW * 2048 + ACC_COL);
; #pragma unroll
;         for (int m = 0; m < 4; ++m)
; #pragma unroll
;           for (int n = 0; n < 2; ++n) {
;             const f32x4 v = acc[ai][bj][m][n];
;             float4 r; r.x = xi[m][n].x + v[0]; r.y = xi[m][n].y + v[1]; r.z = xi[m][n].z + v[2]; r.w = xi[m][n].w + v[3];
;             *reinterpret_cast<float4*>(xout + (size_t)ACC_ROW * 2048 + ACC_COL) = r;
;           }
;         EPI_SCHED;
;       }
	v_readfirstlane_b32 s10, v159
	v_add_u32_e32 v131, s14, v150
	s_mov_b32 m0, s10
	v_readfirstlane_b32 s10, v160
	global_load_lds_dwordx4 v131, s[88:89]
	v_add_u32_e32 v131, s14, v151
	s_mov_b32 m0, s10
	s_nop 0
	global_load_lds_dwordx4 v131, s[88:89]
	v_readfirstlane_b32 s10, v161
	v_add_u32_e32 v131, s13, v150
	s_mov_b32 m0, s10
	v_readfirstlane_b32 s10, v162
	ds_read_b128 v[170:173], v166 offset:49152
	ds_read_b128 v[174:177], v166 offset:50176
	ds_read_b128 v[180:183], v166 offset:51200
	ds_read_b128 v[184:187], v166 offset:52224
	ds_read_b128 v[188:191], v166 offset:53248
	ds_read_b128 v[192:195], v166 offset:54272
	ds_read_b128 v[196:199], v166 offset:55296
	ds_read_b128 v[200:203], v166 offset:56320
	global_load_lds_dwordx4 v131, s[86:87]
	v_add_u32_e32 v131, s13, v151
	s_mov_b32 m0, s10
	s_nop 0
	global_load_lds_dwordx4 v131, s[86:87]
	v_readfirstlane_b32 s10, v163
	v_add_u32_e32 v131, s12, v150
	s_mov_b32 m0, s10
	v_readfirstlane_b32 s10, v165
	global_load_lds_dwordx4 v131, s[88:89]
	v_add_u32_e32 v131, s12, v151
	s_mov_b32 m0, s10
	s_nop 0
	global_load_lds_dwordx4 v131, s[88:89]
	s_waitcnt vmcnt(8)
	s_waitcnt lgkmcnt(0)
	s_barrier
	s_setprio 1
	v_mfma_f32_16x16x32_bf16 v[34:37], v[132:135], v[170:173], v[34:37]
	v_mfma_f32_16x16x32_bf16 v[38:41], v[140:143], v[170:173], v[38:41]
	v_mfma_f32_16x16x32_bf16 v[42:45], v[132:135], v[180:183], v[42:45]
	v_mfma_f32_16x16x32_bf16 v[46:49], v[140:143], v[180:183], v[46:49]
	v_mfma_f32_16x16x32_bf16 v[50:53], v[132:135], v[188:191], v[50:53]
	v_mfma_f32_16x16x32_bf16 v[54:57], v[140:143], v[188:191], v[54:57]
	v_mfma_f32_16x16x32_bf16 v[58:61], v[132:135], v[196:199], v[58:61]
	v_mfma_f32_16x16x32_bf16 v[62:65], v[140:143], v[196:199], v[62:65]
	v_mfma_f32_16x16x32_bf16 v[34:37], v[136:139], v[174:177], v[34:37]
	v_mfma_f32_16x16x32_bf16 v[38:41], v[144:147], v[174:177], v[38:41]
	v_mfma_f32_16x16x32_bf16 v[42:45], v[136:139], v[184:187], v[42:45]
	v_mfma_f32_16x16x32_bf16 v[46:49], v[144:147], v[184:187], v[46:49]
	v_mfma_f32_16x16x32_bf16 v[50:53], v[136:139], v[192:195], v[50:53]
	v_mfma_f32_16x16x32_bf16 v[54:57], v[144:147], v[192:195], v[54:57]
	v_mfma_f32_16x16x32_bf16 v[58:61], v[136:139], v[200:203], v[58:61]
	v_mfma_f32_16x16x32_bf16 v[62:65], v[144:147], v[200:203], v[62:65]
	v_mfma_f32_16x16x32_bf16 v[2:5], v[204:207], v[170:173], v[2:5]
	v_mfma_f32_16x16x32_bf16 v[6:9], v[212:215], v[170:173], v[6:9]
	v_mfma_f32_16x16x32_bf16 v[10:13], v[204:207], v[180:183], v[10:13]
	v_mfma_f32_16x16x32_bf16 v[14:17], v[212:215], v[180:183], v[14:17]
	v_mfma_f32_16x16x32_bf16 v[18:21], v[204:207], v[188:191], v[18:21]
	v_mfma_f32_16x16x32_bf16 v[22:25], v[212:215], v[188:191], v[22:25]
	v_mfma_f32_16x16x32_bf16 v[26:29], v[204:207], v[196:199], v[26:29]
	v_mfma_f32_16x16x32_bf16 v[30:33], v[212:215], v[196:199], v[30:33]
	v_mfma_f32_16x16x32_bf16 v[2:5], v[208:211], v[174:177], v[2:5]
	v_mfma_f32_16x16x32_bf16 v[6:9], v[216:219], v[174:177], v[6:9]
	v_mfma_f32_16x16x32_bf16 v[10:13], v[208:211], v[184:187], v[10:13]
	v_mfma_f32_16x16x32_bf16 v[14:17], v[216:219], v[184:187], v[14:17]
	v_mfma_f32_16x16x32_bf16 v[18:21], v[208:211], v[192:195], v[18:21]
	v_mfma_f32_16x16x32_bf16 v[22:25], v[216:219], v[192:195], v[22:25]
	v_mfma_f32_16x16x32_bf16 v[26:29], v[208:211], v[200:203], v[26:29]
	v_mfma_f32_16x16x32_bf16 v[30:33], v[216:219], v[200:203], v[30:33]
	s_setprio 0
	v_add_u32_e32 v130, 0x100, v130
	s_mov_b32 s10, s11
	s_barrier
	s_cbranch_scc0 .LBB0_132
	v_mov_b32_e32 v131, v239
	s_nop 0
	v_ashrrev_i32_e32 v130, 2, v131
	v_and_b32_e32 v130, 0xffffffc0, v130
	v_and_or_b32 v132, v131, 15, s8
	v_add_u32_e32 v130, v132, v130
	v_lshrrev_b32_e32 v132, 1, v131
	v_lshrrev_b32_e32 v131, 2, v131
	v_and_b32_e32 v132, 0x60, v132
	v_and_b32_e32 v131, 12, v131
	v_or3_b32 v132, v132, v131, s7
	v_ashrrev_i32_e32 v131, 31, v130
	v_ashrrev_i32_e32 v133, 31, v132
	v_lshlrev_b64 v[134:135], 13, v[130:131]
	v_lshl_add_u64 v[136:137], s[48:49], 0, v[134:135]
	v_lshlrev_b64 v[132:133], 2, v[132:133]
	v_lshl_add_u64 v[142:143], v[136:137], 0, v[132:133]
	v_or_b32_e32 v136, 16, v130
	v_ashrrev_i32_e32 v137, 31, v136
	v_lshlrev_b64 v[136:137], 13, v[136:137]
	v_lshl_add_u64 v[138:139], s[48:49], 0, v[136:137]
	v_lshl_add_u64 v[144:145], v[138:139], 0, v[132:133]
	v_or_b32_e32 v138, 32, v130
	v_ashrrev_i32_e32 v139, 31, v138
	v_lshlrev_b64 v[170:171], 13, v[138:139]
	v_lshl_add_u64 v[138:139], s[48:49], 0, v[170:171]
	v_lshl_add_u64 v[146:147], v[138:139], 0, v[132:133]
	v_or_b32_e32 v138, 48, v130
	v_ashrrev_i32_e32 v139, 31, v138
	v_lshlrev_b64 v[172:173], 13, v[138:139]
	v_lshl_add_u64 v[134:135], s[72:73], 0, v[134:135]
	v_lshl_add_u64 v[138:139], s[48:49], 0, v[172:173]
	v_lshl_add_u64 v[140:141], v[134:135], 0, v[132:133]
	v_lshl_add_u64 v[134:135], s[72:73], 0, v[136:137]
	v_lshl_add_u64 v[148:149], v[138:139], 0, v[132:133]
	v_lshl_add_u64 v[138:139], v[134:135], 0, v[132:133]
	v_lshl_add_u64 v[134:135], s[72:73], 0, v[170:171]
	v_lshl_add_u64 v[136:137], v[134:135], 0, v[132:133]
	v_lshl_add_u64 v[134:135], s[72:73], 0, v[172:173]
	global_load_dwordx4 v[170:173], v[148:149], off offset:64
	v_lshl_add_u64 v[134:135], v[134:135], 0, v[132:133]
	s_waitcnt vmcnt(0)
	v_pk_add_f32 v[106:107], v[106:107], v[170:171]
	v_pk_add_f32 v[108:109], v[108:109], v[172:173]
	global_load_dwordx4 v[170:173], v[148:149], off
	s_waitcnt vmcnt(0)
	v_pk_add_f32 v[110:111], v[110:111], v[170:171]
	v_pk_add_f32 v[112:113], v[112:113], v[172:173]
	global_load_dwordx4 v[170:173], v[146:147], off offset:64
	s_waitcnt vmcnt(0)
	v_pk_add_f32 v[114:115], v[114:115], v[170:171]
	v_pk_add_f32 v[116:117], v[116:117], v[172:173]
	global_load_dwordx4 v[170:173], v[146:147], off
	s_waitcnt vmcnt(0)
; #define EPI_SCHED __builtin_amdgcn_sched_barrier(0)
; DI void gemm_resid(const u16* A, const u16* Bt, int K, const float* xin, float* xout, int bid, int nb, int tid) {
;     ...
; #pragma unroll
;     for (int ai = 0; ai < 2; ++ai)
; #pragma unroll
;       for (int bj = 0; bj < 2; ++bj) {
;         float4 xi[4][2];
; #pragma unroll
;         for (int m = 0; m < 4; ++m)
; #pragma unroll
;           for (int n = 0; n < 2; ++n) xi[m][n] = *reinterpret_cast<const float4*>(xin + (size_t)ACC_ROW * 2048 + ACC_COL);
; #pragma unroll
;         for (int m = 0; m < 4; ++m)
; #pragma unroll
;           for (int n = 0; n < 2; ++n) {
;             const f32x4 v = acc[ai][bj][m][n];
;             float4 r; r.x = xi[m][n].x + v[0]; r.y = xi[m][n].y + v[1]; r.z = xi[m][n].z + v[2]; r.w = xi[m][n].w + v[3];
;             *reinterpret_cast<float4*>(xout + (size_t)ACC_ROW * 2048 + ACC_COL) = r;
;           }
;         EPI_SCHED;
;       }
	v_pk_add_f32 v[118:119], v[118:119], v[170:171]
	v_pk_add_f32 v[120:121], v[120:121], v[172:173]
	global_load_dwordx4 v[170:173], v[144:145], off offset:64
	s_waitcnt vmcnt(0)
	v_pk_add_f32 v[122:123], v[122:123], v[170:171]
	v_pk_add_f32 v[124:125], v[124:125], v[172:173]
	global_load_dwordx4 v[170:173], v[144:145], off
	s_waitcnt vmcnt(0)
	v_pk_add_f32 v[126:127], v[126:127], v[170:171]
	v_pk_add_f32 v[128:129], v[128:129], v[172:173]
	global_load_dwordx4 v[170:173], v[142:143], off offset:64
	s_waitcnt vmcnt(0)
	v_pk_add_f32 v[102:103], v[102:103], v[170:171]
	v_pk_add_f32 v[104:105], v[104:105], v[172:173]
	global_load_dwordx4 v[170:173], v[142:143], off
	s_waitcnt vmcnt(0)
	v_pk_add_f32 v[98:99], v[98:99], v[170:171]
	v_pk_add_f32 v[100:101], v[100:101], v[172:173]
	global_store_dwordx4 v[140:141], v[98:101], off
	global_store_dwordx4 v[140:141], v[102:105], off offset:64
	global_store_dwordx4 v[138:139], v[126:129], off
	global_store_dwordx4 v[138:139], v[122:125], off offset:64
	global_store_dwordx4 v[136:137], v[118:121], off
	global_store_dwordx4 v[136:137], v[114:117], off offset:64
	global_store_dwordx4 v[134:135], v[110:113], off
	global_store_dwordx4 v[134:135], v[106:109], off offset:64
	global_load_dwordx4 v[98:101], v[148:149], off offset:576
	s_waitcnt vmcnt(0)
	v_pk_add_f32 v[94:95], v[94:95], v[98:99]
	v_pk_add_f32 v[96:97], v[96:97], v[100:101]
	global_load_dwordx4 v[98:101], v[148:149], off offset:512
	s_waitcnt vmcnt(0)
	v_pk_add_f32 v[90:91], v[90:91], v[98:99]
	v_pk_add_f32 v[92:93], v[92:93], v[100:101]
	global_load_dwordx4 v[98:101], v[146:147], off offset:576
	s_waitcnt vmcnt(0)
	v_pk_add_f32 v[86:87], v[86:87], v[98:99]
	v_pk_add_f32 v[88:89], v[88:89], v[100:101]
	global_load_dwordx4 v[98:101], v[146:147], off offset:512
	s_waitcnt vmcnt(0)
	v_pk_add_f32 v[82:83], v[82:83], v[98:99]
	v_pk_add_f32 v[84:85], v[84:85], v[100:101]
	global_load_dwordx4 v[98:101], v[144:145], off offset:576
	s_waitcnt vmcnt(0)
	v_pk_add_f32 v[78:79], v[78:79], v[98:99]
	v_pk_add_f32 v[80:81], v[80:81], v[100:101]
	global_load_dwordx4 v[98:101], v[144:145], off offset:512
	s_waitcnt vmcnt(0)
	v_pk_add_f32 v[74:75], v[74:75], v[98:99]
	v_pk_add_f32 v[76:77], v[76:77], v[100:101]
	global_load_dwordx4 v[98:101], v[142:143], off offset:576
	s_waitcnt vmcnt(0)
	v_pk_add_f32 v[70:71], v[70:71], v[98:99]
	v_pk_add_f32 v[72:73], v[72:73], v[100:101]
	global_load_dwordx4 v[98:101], v[142:143], off offset:512
	s_waitcnt vmcnt(0)
	v_pk_add_f32 v[66:67], v[66:67], v[98:99]
	v_pk_add_f32 v[68:69], v[68:69], v[100:101]
	global_store_dwordx4 v[140:141], v[66:69], off offset:512
	global_store_dwordx4 v[140:141], v[70:73], off offset:576
	global_store_dwordx4 v[138:139], v[74:77], off offset:512
	global_store_dwordx4 v[138:139], v[78:81], off offset:576
	global_store_dwordx4 v[136:137], v[82:85], off offset:512
	global_store_dwordx4 v[136:137], v[86:89], off offset:576
	global_store_dwordx4 v[134:135], v[90:93], off offset:512
	global_store_dwordx4 v[134:135], v[94:97], off offset:576
	v_add_u32_e32 v66, 0x80, v130
	v_ashrrev_i32_e32 v67, 31, v66
	v_lshlrev_b64 v[66:67], 13, v[66:67]
	v_lshl_add_u64 v[68:69], s[48:49], 0, v[66:67]
	v_lshl_add_u64 v[74:75], v[68:69], 0, v[132:133]
	v_add_u32_e32 v68, 0x90, v130
	v_ashrrev_i32_e32 v69, 31, v68
	v_lshlrev_b64 v[68:69], 13, v[68:69]
	v_lshl_add_u64 v[70:71], s[48:49], 0, v[68:69]
	v_lshl_add_u64 v[76:77], v[70:71], 0, v[132:133]
	v_add_u32_e32 v70, 0xa0, v130
	v_ashrrev_i32_e32 v71, 31, v70
	v_lshlrev_b64 v[82:83], 13, v[70:71]
	v_lshl_add_u64 v[70:71], s[48:49], 0, v[82:83]
	v_lshl_add_u64 v[78:79], v[70:71], 0, v[132:133]
	v_add_u32_e32 v70, 0xb0, v130
	v_ashrrev_i32_e32 v71, 31, v70
	v_lshlrev_b64 v[84:85], 13, v[70:71]
	v_lshl_add_u64 v[66:67], s[72:73], 0, v[66:67]
	v_lshl_add_u64 v[70:71], s[48:49], 0, v[84:85]
	v_lshl_add_u64 v[72:73], v[66:67], 0, v[132:133]
	v_lshl_add_u64 v[66:67], s[72:73], 0, v[68:69]
	v_lshl_add_u64 v[80:81], v[70:71], 0, v[132:133]
	v_lshl_add_u64 v[70:71], v[66:67], 0, v[132:133]
	v_lshl_add_u64 v[66:67], s[72:73], 0, v[82:83]
	v_lshl_add_u64 v[68:69], v[66:67], 0, v[132:133]
	v_lshl_add_u64 v[66:67], s[72:73], 0, v[84:85]
	global_load_dwordx4 v[82:85], v[80:81], off offset:64
	v_lshl_add_u64 v[66:67], v[66:67], 0, v[132:133]
	s_waitcnt vmcnt(0)
; #define WAIT_V(n) asm volatile("s_waitcnt vmcnt(" #n ")" ::: "memory")
; #define BAR __builtin_amdgcn_s_barrier()
; #define EPI_SCHED __builtin_amdgcn_sched_barrier(0)
; template <class EPI>
; DI void gemm_stream(const u16* __restrict__ A, const u16* __restrict__ Bt, const int K, const int nM, const int nN,
;                     const int bid, const int nb, const int tid, EPI epi) {
;     ...
;     brow = brow2; bcol = bcol2; pm = pm2; pn = pn2;
;   }
;   WAIT_V(0);
;   if (wr == 0) BAR;
;   BAR;
; DI void gemm_resid(const u16* A, const u16* Bt, int K, const float* xin, float* xout, int bid, int nb, int tid) {
;     ...
; #pragma unroll
;     for (int ai = 0; ai < 2; ++ai)
; #pragma unroll
;       for (int bj = 0; bj < 2; ++bj) {
;         float4 xi[4][2];
; #pragma unroll
;         for (int m = 0; m < 4; ++m)
; #pragma unroll
;           for (int n = 0; n < 2; ++n) xi[m][n] = *reinterpret_cast<const float4*>(xin + (size_t)ACC_ROW * 2048 + ACC_COL);
; #pragma unroll
;         for (int m = 0; m < 4; ++m)
; #pragma unroll
;           for (int n = 0; n < 2; ++n) {
;             const f32x4 v = acc[ai][bj][m][n];
;             float4 r; r.x = xi[m][n].x + v[0]; r.y = xi[m][n].y + v[1]; r.z = xi[m][n].z + v[2]; r.w = xi[m][n].w + v[3];
;             *reinterpret_cast<float4*>(xout + (size_t)ACC_ROW * 2048 + ACC_COL) = r;
;           }
;         EPI_SCHED;
;       }
	v_pk_add_f32 v[62:63], v[62:63], v[82:83]
	v_pk_add_f32 v[64:65], v[64:65], v[84:85]
	global_load_dwordx4 v[82:85], v[80:81], off
	s_waitcnt vmcnt(0)
	v_pk_add_f32 v[58:59], v[58:59], v[82:83]
	v_pk_add_f32 v[60:61], v[60:61], v[84:85]
	global_load_dwordx4 v[82:85], v[78:79], off offset:64
	s_waitcnt vmcnt(0)
	v_pk_add_f32 v[54:55], v[54:55], v[82:83]
	v_pk_add_f32 v[56:57], v[56:57], v[84:85]
	global_load_dwordx4 v[82:85], v[78:79], off
	s_waitcnt vmcnt(0)
	v_pk_add_f32 v[50:51], v[50:51], v[82:83]
	v_pk_add_f32 v[52:53], v[52:53], v[84:85]
	global_load_dwordx4 v[82:85], v[76:77], off offset:64
	s_waitcnt vmcnt(0)
	v_pk_add_f32 v[46:47], v[46:47], v[82:83]
	v_pk_add_f32 v[48:49], v[48:49], v[84:85]
	global_load_dwordx4 v[82:85], v[76:77], off
	s_waitcnt vmcnt(0)
	v_pk_add_f32 v[42:43], v[42:43], v[82:83]
	v_pk_add_f32 v[44:45], v[44:45], v[84:85]
	global_load_dwordx4 v[82:85], v[74:75], off offset:64
	s_waitcnt vmcnt(0)
	v_pk_add_f32 v[38:39], v[38:39], v[82:83]
	v_pk_add_f32 v[40:41], v[40:41], v[84:85]
	global_load_dwordx4 v[82:85], v[74:75], off
	s_waitcnt vmcnt(0)
	v_pk_add_f32 v[34:35], v[34:35], v[82:83]
	v_pk_add_f32 v[36:37], v[36:37], v[84:85]
	global_store_dwordx4 v[72:73], v[34:37], off
	global_store_dwordx4 v[72:73], v[38:41], off offset:64
	global_store_dwordx4 v[70:71], v[42:45], off
	global_store_dwordx4 v[70:71], v[46:49], off offset:64
	global_store_dwordx4 v[68:69], v[50:53], off
	global_store_dwordx4 v[68:69], v[54:57], off offset:64
	global_store_dwordx4 v[66:67], v[58:61], off
	global_store_dwordx4 v[66:67], v[62:65], off offset:64
	global_load_dwordx4 v[34:37], v[80:81], off offset:576
	s_waitcnt vmcnt(0)
	v_pk_add_f32 v[30:31], v[30:31], v[34:35]
	v_pk_add_f32 v[32:33], v[32:33], v[36:37]
	global_load_dwordx4 v[34:37], v[80:81], off offset:512
	s_waitcnt vmcnt(0)
	v_pk_add_f32 v[26:27], v[26:27], v[34:35]
	v_pk_add_f32 v[28:29], v[28:29], v[36:37]
	global_load_dwordx4 v[34:37], v[78:79], off offset:576
	s_waitcnt vmcnt(0)
	v_pk_add_f32 v[22:23], v[22:23], v[34:35]
	v_pk_add_f32 v[24:25], v[24:25], v[36:37]
	global_load_dwordx4 v[34:37], v[78:79], off offset:512
	s_waitcnt vmcnt(0)
	v_pk_add_f32 v[18:19], v[18:19], v[34:35]
	v_pk_add_f32 v[20:21], v[20:21], v[36:37]
	global_load_dwordx4 v[34:37], v[76:77], off offset:576
	s_waitcnt vmcnt(0)
	v_pk_add_f32 v[14:15], v[14:15], v[34:35]
	v_pk_add_f32 v[16:17], v[16:17], v[36:37]
	global_load_dwordx4 v[34:37], v[76:77], off offset:512
	s_waitcnt vmcnt(0)
	v_pk_add_f32 v[10:11], v[10:11], v[34:35]
	v_pk_add_f32 v[12:13], v[12:13], v[36:37]
	global_load_dwordx4 v[34:37], v[74:75], off offset:576
	s_waitcnt vmcnt(0)
	v_pk_add_f32 v[6:7], v[6:7], v[34:35]
	v_pk_add_f32 v[8:9], v[8:9], v[36:37]
	global_load_dwordx4 v[34:37], v[74:75], off offset:512
	s_waitcnt vmcnt(0)
	v_pk_add_f32 v[2:3], v[2:3], v[34:35]
	v_pk_add_f32 v[4:5], v[4:5], v[36:37]
	global_store_dwordx4 v[72:73], v[2:5], off offset:512
	global_store_dwordx4 v[72:73], v[6:9], off offset:576
	global_store_dwordx4 v[70:71], v[10:13], off offset:512
	global_store_dwordx4 v[70:71], v[14:17], off offset:576
	global_store_dwordx4 v[68:69], v[18:21], off offset:512
	global_store_dwordx4 v[68:69], v[22:25], off offset:576
	global_store_dwordx4 v[66:67], v[26:29], off offset:512
	global_store_dwordx4 v[66:67], v[30:33], off offset:576
	s_and_b64 vcc, exec, s[0:1]
	s_mov_b32 s8, s5
	s_mov_b32 s7, s6
	s_cbranch_vccz .LBB0_129
	s_waitcnt vmcnt(0)
	s_movk_i32 s0, 0x100
	v_cmp_gt_u32_e32 vcc, s0, v239
	s_and_saveexec_b64 s[0:1], vcc
	s_cbranch_execz .LBB0_136
	s_barrier

.Lpj48_loop:
	v_or_b32_e32 v122, 0x10000, v200
	v_add_u32_e32 v134, 0x10400, v200
	v_add_u32_e32 v138, 0x10800, v200
	v_add_u32_e32 v142, 0x10c00, v200
	ds_read_b128 v[122:125], v122
	ds_read_b128 v[134:137], v134
	ds_read_b128 v[138:141], v138
	ds_read_b128 v[142:145], v142
	s_add_i32 s1, s0, -2
	s_cmp_lt_u32 s1, 30
	s_cselect_b32 s3, s4, s16
	s_cselect_b32 s5, s2, s15
	v_add_u32_e32 v181, 0xc000, v179
	v_add_u32_e32 v180, 0xfffc0000, v0
	v_readfirstlane_b32 s6, v181
	s_mov_b32 m0, s6
	ds_read_b128 v[146:149], v199
	ds_read_b128 v[150:153], v199 offset:1024
	ds_read_b128 v[154:157], v199 offset:2048
	ds_read_b128 v[158:161], v199 offset:3072
	ds_read_b128 v[162:165], v199 offset:4096
	ds_read_b128 v[166:169], v199 offset:5120
	ds_read_b128 v[170:173], v199 offset:6144
	ds_read_b128 v[174:177], v199 offset:7168
	global_load_lds_dwordx4 v180, s[80:81]
	v_add_u32_e32 v180, 0xe000, v179
	s_nop 0
	v_readfirstlane_b32 s6, v180
	s_mov_b32 m0, s6
	s_nop 0
	global_load_lds_dwordx4 v0, s[80:81]
	v_or_b32_e32 v180, 0x14000, v200
	v_add_u32_e32 v202, 0x14400, v200
	v_add_u32_e32 v206, 0x14800, v200
	v_add_u32_e32 v210, 0x14c00, v200
	ds_read_b128 v[180:183], v180
	ds_read_b128 v[202:205], v202
	ds_read_b128 v[206:209], v206
	ds_read_b128 v[210:213], v210
	s_waitcnt vmcnt(8)
	s_waitcnt lgkmcnt(0)
	s_barrier
	s_setprio 1
	v_mfma_f32_16x16x32_bf16 v[130:133], v[122:125], v[146:149], v[130:133]
	v_mfma_f32_16x16x32_bf16 v[110:113], v[122:125], v[154:157], v[110:113]
	v_mfma_f32_16x16x32_bf16 v[94:97], v[122:125], v[162:165], v[94:97]
	v_mfma_f32_16x16x32_bf16 v[78:81], v[122:125], v[170:173], v[78:81]
	v_mfma_f32_16x16x32_bf16 v[130:133], v[134:137], v[150:153], v[130:133]
	v_mfma_f32_16x16x32_bf16 v[110:113], v[134:137], v[158:161], v[110:113]
	v_mfma_f32_16x16x32_bf16 v[94:97], v[134:137], v[166:169], v[94:97]
	v_mfma_f32_16x16x32_bf16 v[78:81], v[134:137], v[174:177], v[78:81]
	s_setprio 0
	s_barrier
	s_cselect_b32 s6, s0, 0
	s_lshl_b32 s3, s3, 11
	s_lshl_b32 s7, s6, 6
	s_or_b32 s10, s3, s7
	s_lshl_b32 s10, s10, 1
	v_readfirstlane_b32 s11, v186
	v_add_u32_e32 v214, s10, v184
	s_mov_b32 m0, s11
	global_load_lds_dwordx4 v214, s[74:75]
	v_add_u32_e32 v214, s10, v185
	v_readfirstlane_b32 s10, v187
	s_mov_b32 m0, s10
	s_nop 0
	global_load_lds_dwordx4 v214, s[74:75]
	s_lshl_b32 s10, s5, 11
	s_or_b32 s11, s10, s7
	s_lshl_b32 s11, s11, 1
	v_readfirstlane_b32 s18, v179
	v_add_u32_e32 v214, s11, v184
	s_mov_b32 m0, s18
	ds_read_b128 v[146:149], v199 offset:16384
	ds_read_b128 v[150:153], v199 offset:17408
	ds_read_b128 v[154:157], v199 offset:18432
	ds_read_b128 v[158:161], v199 offset:19456
	ds_read_b128 v[162:165], v199 offset:20480
	ds_read_b128 v[166:169], v199 offset:21504
	ds_read_b128 v[170:173], v199 offset:22528
	ds_read_b128 v[174:177], v199 offset:23552
	global_load_lds_dwordx4 v214, s[80:81]
	v_add_u32_e32 v214, s11, v185
	v_readfirstlane_b32 s11, v188
	s_mov_b32 m0, s11
	s_nop 0
	global_load_lds_dwordx4 v214, s[80:81]
	s_or_b32 s11, s3, 0x40000
	s_or_b32 s18, s11, s7
	s_lshl_b32 s18, s18, 1
	v_readfirstlane_b32 s19, v189
	v_add_u32_e32 v215, s18, v184
	s_mov_b32 m0, s19
	s_nop 0
	global_load_lds_dwordx4 v215, s[74:75]
	v_add_u32_e32 v215, s18, v185
	v_readfirstlane_b32 s18, v190
	s_mov_b32 m0, s18
	s_nop 0
	global_load_lds_dwordx4 v215, s[74:75]
	s_waitcnt vmcnt(8)
	s_waitcnt lgkmcnt(0)
	s_barrier
	s_setprio 1
	v_mfma_f32_16x16x32_bf16 v[62:65], v[122:125], v[146:149], v[62:65]
	v_mfma_f32_16x16x32_bf16 v[46:49], v[122:125], v[154:157], v[46:49]
	v_mfma_f32_16x16x32_bf16 v[30:33], v[122:125], v[162:165], v[30:33]
	v_mfma_f32_16x16x32_bf16 v[14:17], v[122:125], v[170:173], v[14:17]
	v_mfma_f32_16x16x32_bf16 v[62:65], v[134:137], v[150:153], v[62:65]
	v_mfma_f32_16x16x32_bf16 v[46:49], v[134:137], v[158:161], v[46:49]
	v_mfma_f32_16x16x32_bf16 v[30:33], v[134:137], v[166:169], v[30:33]
	v_mfma_f32_16x16x32_bf16 v[14:17], v[134:137], v[174:177], v[14:17]
	s_setprio 0
	s_barrier
	v_or_b32_e32 v122, 0x18000, v200
	v_add_u32_e32 v134, 0x18400, v200
	v_add_u32_e32 v138, 0x18800, v200
	v_add_u32_e32 v142, 0x18c00, v200
	ds_read_b128 v[122:125], v122
	ds_read_b128 v[134:137], v134
	ds_read_b128 v[138:141], v138
	ds_read_b128 v[142:145], v142
	s_lshl_b32 s5, s5, 12
	s_lshl_b32 s6, s6, 7
	s_add_i32 s5, s6, s5
	s_add_i32 s5, s5, 0x80000
	v_readfirstlane_b32 s6, v191
	v_add_u32_e32 v180, s5, v184
	s_mov_b32 m0, s6
	ds_read_b128 v[146:149], v199 offset:32768
	ds_read_b128 v[150:153], v199 offset:33792
	ds_read_b128 v[154:157], v199 offset:34816
	ds_read_b128 v[158:161], v199 offset:35840
	ds_read_b128 v[162:165], v199 offset:36864
	ds_read_b128 v[166:169], v199 offset:37888
	ds_read_b128 v[170:173], v199 offset:38912
	ds_read_b128 v[174:177], v199 offset:39936
	global_load_lds_dwordx4 v180, s[80:81]
	v_add_u32_e32 v180, s5, v185
	v_readfirstlane_b32 s5, v192
	s_mov_b32 m0, s5
	s_nop 0
	global_load_lds_dwordx4 v180, s[80:81]
	v_or_b32_e32 v180, 0x1c000, v200
	v_add_u32_e32 v202, 0x1c400, v200
	v_add_u32_e32 v206, 0x1c800, v200
	v_add_u32_e32 v210, 0x1cc00, v200
	ds_read_b128 v[180:183], v180
	ds_read_b128 v[202:205], v202
	ds_read_b128 v[206:209], v206
	ds_read_b128 v[210:213], v210
	s_waitcnt vmcnt(8)
	s_waitcnt lgkmcnt(0)
	s_barrier
	s_setprio 1
	v_mfma_f32_16x16x32_bf16 v[130:133], v[122:125], v[146:149], v[130:133]
	v_mfma_f32_16x16x32_bf16 v[110:113], v[122:125], v[154:157], v[110:113]
	v_mfma_f32_16x16x32_bf16 v[94:97], v[122:125], v[162:165], v[94:97]
	v_mfma_f32_16x16x32_bf16 v[78:81], v[122:125], v[170:173], v[78:81]
	v_mfma_f32_16x16x32_bf16 v[130:133], v[134:137], v[150:153], v[130:133]
	v_mfma_f32_16x16x32_bf16 v[110:113], v[134:137], v[158:161], v[110:113]
	v_mfma_f32_16x16x32_bf16 v[94:97], v[134:137], v[166:169], v[94:97]
	v_mfma_f32_16x16x32_bf16 v[78:81], v[134:137], v[174:177], v[78:81]
	s_setprio 0
	s_barrier
	s_or_b32 s5, s7, 64
	s_or_b32 s3, s5, s3
	s_lshl_b32 s3, s3, 1
	v_readfirstlane_b32 s6, v193
	v_add_u32_e32 v214, s3, v184
	s_mov_b32 m0, s6
	global_load_lds_dwordx4 v214, s[74:75]
	v_add_u32_e32 v214, s3, v185
	v_readfirstlane_b32 s3, v194
	s_mov_b32 m0, s3
	s_nop 0
	global_load_lds_dwordx4 v214, s[74:75]
	s_or_b32 s3, s5, s10
	s_lshl_b32 s3, s3, 1
	v_readfirstlane_b32 s6, v195
	v_add_u32_e32 v214, s3, v184
	s_mov_b32 m0, s6
	ds_read_b128 v[146:149], v199 offset:49152
	ds_read_b128 v[150:153], v199 offset:50176
	ds_read_b128 v[154:157], v199 offset:51200
	ds_read_b128 v[158:161], v199 offset:52224
	ds_read_b128 v[162:165], v199 offset:53248
	ds_read_b128 v[166:169], v199 offset:54272
	ds_read_b128 v[170:173], v199 offset:55296
	ds_read_b128 v[174:177], v199 offset:56320
	global_load_lds_dwordx4 v214, s[80:81]
	v_add_u32_e32 v214, s3, v185
	v_readfirstlane_b32 s3, v196
	s_mov_b32 m0, s3
	s_nop 0
	global_load_lds_dwordx4 v214, s[80:81]
	s_or_b32 s3, s11, s5
	s_lshl_b32 s3, s3, 1
	v_readfirstlane_b32 s5, v197
	v_add_u32_e32 v215, s3, v184
	s_mov_b32 m0, s5
	s_nop 0
	global_load_lds_dwordx4 v215, s[74:75]
	v_add_u32_e32 v215, s3, v185
	v_readfirstlane_b32 s3, v198
	s_mov_b32 m0, s3
	s_nop 0
	global_load_lds_dwordx4 v215, s[74:75]
	s_waitcnt vmcnt(8)
	s_waitcnt lgkmcnt(0)
	s_barrier
	s_setprio 1
	v_mfma_f32_16x16x32_bf16 v[62:65], v[122:125], v[146:149], v[62:65]
	v_mfma_f32_16x16x32_bf16 v[46:49], v[122:125], v[154:157], v[46:49]
	v_mfma_f32_16x16x32_bf16 v[30:33], v[122:125], v[162:165], v[30:33]
	v_mfma_f32_16x16x32_bf16 v[14:17], v[122:125], v[170:173], v[14:17]
	v_mfma_f32_16x16x32_bf16 v[62:65], v[134:137], v[150:153], v[62:65]
	v_mfma_f32_16x16x32_bf16 v[46:49], v[134:137], v[158:161], v[46:49]
	v_mfma_f32_16x16x32_bf16 v[30:33], v[134:137], v[166:169], v[30:33]
	v_mfma_f32_16x16x32_bf16 v[14:17], v[134:137], v[174:177], v[14:17]
	s_setprio 0
	s_add_i32 s0, s0, 2
	s_cmp_gt_u32 s1, 29
	v_add_u32_e32 v0, 0x100, v0
	s_barrier
	s_cbranch_scc0 .Lpj48_loop
	s_branch .Lpj48_done

.LBB0_414:
	v_or_b32_e32 v122, 0x10000, v200
	v_add_u32_e32 v134, 0x10400, v200
	v_add_u32_e32 v138, 0x10800, v200
	v_add_u32_e32 v142, 0x10c00, v200
	ds_read_b128 v[122:125], v122
	ds_read_b128 v[134:137], v134
	ds_read_b128 v[138:141], v138
	ds_read_b128 v[142:145], v142
	s_add_i32 s1, s0, -2
	s_cmp_lt_u32 s1, 30
	s_cselect_b32 s3, s4, s16
	s_cselect_b32 s5, s2, s15
	v_add_u32_e32 v181, 0xc000, v179
	v_add_u32_e32 v180, 0xfffc0000, v0
	v_readfirstlane_b32 s6, v181
	s_mov_b32 m0, s6
	ds_read_b128 v[146:149], v199
	ds_read_b128 v[150:153], v199 offset:1024
	ds_read_b128 v[154:157], v199 offset:2048
	ds_read_b128 v[158:161], v199 offset:3072
	ds_read_b128 v[162:165], v199 offset:4096
	ds_read_b128 v[166:169], v199 offset:5120
	ds_read_b128 v[170:173], v199 offset:6144
	ds_read_b128 v[174:177], v199 offset:7168
	global_load_lds_dwordx4 v180, s[80:81]
	v_add_u32_e32 v180, 0xe000, v179
	s_nop 0
	v_readfirstlane_b32 s6, v180
	s_mov_b32 m0, s6
	s_nop 0
	global_load_lds_dwordx4 v0, s[80:81]
	v_or_b32_e32 v180, 0x14000, v200
	v_add_u32_e32 v202, 0x14400, v200
	v_add_u32_e32 v206, 0x14800, v200
	v_add_u32_e32 v210, 0x14c00, v200
	ds_read_b128 v[180:183], v180
	ds_read_b128 v[202:205], v202
	ds_read_b128 v[206:209], v206
	ds_read_b128 v[210:213], v210
	s_waitcnt vmcnt(8)
	s_waitcnt lgkmcnt(0)
	s_barrier
	s_setprio 1
	v_mfma_f32_16x16x32_bf16 v[130:133], v[122:125], v[146:149], v[130:133]
	v_mfma_f32_16x16x32_bf16 v[126:129], v[138:141], v[146:149], v[126:129]
	v_mfma_f32_16x16x32_bf16 v[110:113], v[122:125], v[154:157], v[110:113]
	v_mfma_f32_16x16x32_bf16 v[106:109], v[138:141], v[154:157], v[106:109]
	v_mfma_f32_16x16x32_bf16 v[94:97], v[122:125], v[162:165], v[94:97]
	v_mfma_f32_16x16x32_bf16 v[90:93], v[138:141], v[162:165], v[90:93]
	v_mfma_f32_16x16x32_bf16 v[78:81], v[122:125], v[170:173], v[78:81]
	v_mfma_f32_16x16x32_bf16 v[74:77], v[138:141], v[170:173], v[74:77]
	v_mfma_f32_16x16x32_bf16 v[130:133], v[134:137], v[150:153], v[130:133]
	v_mfma_f32_16x16x32_bf16 v[126:129], v[142:145], v[150:153], v[126:129]
	v_mfma_f32_16x16x32_bf16 v[110:113], v[134:137], v[158:161], v[110:113]
	v_mfma_f32_16x16x32_bf16 v[106:109], v[142:145], v[158:161], v[106:109]
	v_mfma_f32_16x16x32_bf16 v[94:97], v[134:137], v[166:169], v[94:97]
	v_mfma_f32_16x16x32_bf16 v[90:93], v[142:145], v[166:169], v[90:93]
	v_mfma_f32_16x16x32_bf16 v[78:81], v[134:137], v[174:177], v[78:81]
	v_mfma_f32_16x16x32_bf16 v[74:77], v[142:145], v[174:177], v[74:77]
	v_mfma_f32_16x16x32_bf16 v[118:121], v[180:183], v[146:149], v[118:121]
	v_mfma_f32_16x16x32_bf16 v[114:117], v[206:209], v[146:149], v[114:117]
	v_mfma_f32_16x16x32_bf16 v[102:105], v[180:183], v[154:157], v[102:105]
	v_mfma_f32_16x16x32_bf16 v[98:101], v[206:209], v[154:157], v[98:101]
	v_mfma_f32_16x16x32_bf16 v[86:89], v[180:183], v[162:165], v[86:89]
	v_mfma_f32_16x16x32_bf16 v[82:85], v[206:209], v[162:165], v[82:85]
	v_mfma_f32_16x16x32_bf16 v[70:73], v[180:183], v[170:173], v[70:73]
	v_mfma_f32_16x16x32_bf16 v[66:69], v[206:209], v[170:173], v[66:69]
	v_mfma_f32_16x16x32_bf16 v[118:121], v[202:205], v[150:153], v[118:121]
	v_mfma_f32_16x16x32_bf16 v[114:117], v[210:213], v[150:153], v[114:117]
	v_mfma_f32_16x16x32_bf16 v[102:105], v[202:205], v[158:161], v[102:105]
	v_mfma_f32_16x16x32_bf16 v[98:101], v[210:213], v[158:161], v[98:101]
	v_mfma_f32_16x16x32_bf16 v[86:89], v[202:205], v[166:169], v[86:89]
	v_mfma_f32_16x16x32_bf16 v[82:85], v[210:213], v[166:169], v[82:85]
	v_mfma_f32_16x16x32_bf16 v[70:73], v[202:205], v[174:177], v[70:73]
	v_mfma_f32_16x16x32_bf16 v[66:69], v[210:213], v[174:177], v[66:69]
	s_setprio 0
	s_barrier
	s_cselect_b32 s6, s0, 0
	s_lshl_b32 s3, s3, 11
	s_lshl_b32 s7, s6, 6
	s_or_b32 s10, s3, s7
	s_lshl_b32 s10, s10, 1
	v_readfirstlane_b32 s11, v186
	v_add_u32_e32 v214, s10, v184
	s_mov_b32 m0, s11
	global_load_lds_dwordx4 v214, s[74:75]
	v_add_u32_e32 v214, s10, v185
	v_readfirstlane_b32 s10, v187
	s_mov_b32 m0, s10
	s_nop 0
	global_load_lds_dwordx4 v214, s[74:75]
	s_lshl_b32 s10, s5, 11
	s_or_b32 s11, s10, s7
	s_lshl_b32 s11, s11, 1
	v_readfirstlane_b32 s18, v179
	v_add_u32_e32 v214, s11, v184
	s_mov_b32 m0, s18
	ds_read_b128 v[146:149], v199 offset:16384
	ds_read_b128 v[150:153], v199 offset:17408
	ds_read_b128 v[154:157], v199 offset:18432
	ds_read_b128 v[158:161], v199 offset:19456
	ds_read_b128 v[162:165], v199 offset:20480
	ds_read_b128 v[166:169], v199 offset:21504
	ds_read_b128 v[170:173], v199 offset:22528
	ds_read_b128 v[174:177], v199 offset:23552
	global_load_lds_dwordx4 v214, s[80:81]
	v_add_u32_e32 v214, s11, v185
	v_readfirstlane_b32 s11, v188
	s_mov_b32 m0, s11
	s_nop 0
	global_load_lds_dwordx4 v214, s[80:81]
	s_or_b32 s11, s3, 0x40000
	s_or_b32 s18, s11, s7
	s_lshl_b32 s18, s18, 1
	v_readfirstlane_b32 s19, v189
	v_add_u32_e32 v215, s18, v184
	s_mov_b32 m0, s19
	s_nop 0
	global_load_lds_dwordx4 v215, s[74:75]
	v_add_u32_e32 v215, s18, v185
	v_readfirstlane_b32 s18, v190
	s_mov_b32 m0, s18
	s_nop 0
	global_load_lds_dwordx4 v215, s[74:75]
	s_waitcnt vmcnt(8)
	s_waitcnt lgkmcnt(0)
	s_barrier
	s_setprio 1
	v_mfma_f32_16x16x32_bf16 v[62:65], v[122:125], v[146:149], v[62:65]
	v_mfma_f32_16x16x32_bf16 v[58:61], v[138:141], v[146:149], v[58:61]
	v_mfma_f32_16x16x32_bf16 v[46:49], v[122:125], v[154:157], v[46:49]
	v_mfma_f32_16x16x32_bf16 v[42:45], v[138:141], v[154:157], v[42:45]
	v_mfma_f32_16x16x32_bf16 v[30:33], v[122:125], v[162:165], v[30:33]
	v_mfma_f32_16x16x32_bf16 v[26:29], v[138:141], v[162:165], v[26:29]
	v_mfma_f32_16x16x32_bf16 v[14:17], v[122:125], v[170:173], v[14:17]
	v_mfma_f32_16x16x32_bf16 v[10:13], v[138:141], v[170:173], v[10:13]
	v_mfma_f32_16x16x32_bf16 v[62:65], v[134:137], v[150:153], v[62:65]
	v_mfma_f32_16x16x32_bf16 v[58:61], v[142:145], v[150:153], v[58:61]
	v_mfma_f32_16x16x32_bf16 v[46:49], v[134:137], v[158:161], v[46:49]
	v_mfma_f32_16x16x32_bf16 v[42:45], v[142:145], v[158:161], v[42:45]
	v_mfma_f32_16x16x32_bf16 v[30:33], v[134:137], v[166:169], v[30:33]
	v_mfma_f32_16x16x32_bf16 v[26:29], v[142:145], v[166:169], v[26:29]
	v_mfma_f32_16x16x32_bf16 v[14:17], v[134:137], v[174:177], v[14:17]
	v_mfma_f32_16x16x32_bf16 v[10:13], v[142:145], v[174:177], v[10:13]
	v_mfma_f32_16x16x32_bf16 v[54:57], v[180:183], v[146:149], v[54:57]
	v_mfma_f32_16x16x32_bf16 v[50:53], v[206:209], v[146:149], v[50:53]
	v_mfma_f32_16x16x32_bf16 v[38:41], v[180:183], v[154:157], v[38:41]
	v_mfma_f32_16x16x32_bf16 v[34:37], v[206:209], v[154:157], v[34:37]
	v_mfma_f32_16x16x32_bf16 v[22:25], v[180:183], v[162:165], v[22:25]
	v_mfma_f32_16x16x32_bf16 v[18:21], v[206:209], v[162:165], v[18:21]
	v_mfma_f32_16x16x32_bf16 v[6:9], v[180:183], v[170:173], v[6:9]
	v_mfma_f32_16x16x32_bf16 v[2:5], v[206:209], v[170:173], v[2:5]
	v_mfma_f32_16x16x32_bf16 v[54:57], v[202:205], v[150:153], v[54:57]
	v_mfma_f32_16x16x32_bf16 v[50:53], v[210:213], v[150:153], v[50:53]
	v_mfma_f32_16x16x32_bf16 v[38:41], v[202:205], v[158:161], v[38:41]
	v_mfma_f32_16x16x32_bf16 v[34:37], v[210:213], v[158:161], v[34:37]
	v_mfma_f32_16x16x32_bf16 v[22:25], v[202:205], v[166:169], v[22:25]
	v_mfma_f32_16x16x32_bf16 v[18:21], v[210:213], v[166:169], v[18:21]
	v_mfma_f32_16x16x32_bf16 v[6:9], v[202:205], v[174:177], v[6:9]
	v_mfma_f32_16x16x32_bf16 v[2:5], v[210:213], v[174:177], v[2:5]
	s_setprio 0
	s_barrier
	v_or_b32_e32 v122, 0x18000, v200
	v_add_u32_e32 v134, 0x18400, v200
	v_add_u32_e32 v138, 0x18800, v200
	v_add_u32_e32 v142, 0x18c00, v200
	ds_read_b128 v[122:125], v122
	ds_read_b128 v[134:137], v134
	ds_read_b128 v[138:141], v138
	ds_read_b128 v[142:145], v142
	s_lshl_b32 s5, s5, 12
	s_lshl_b32 s6, s6, 7
	s_add_i32 s5, s6, s5
	s_add_i32 s5, s5, 0x80000
	v_readfirstlane_b32 s6, v191
	v_add_u32_e32 v180, s5, v184
	s_mov_b32 m0, s6
	ds_read_b128 v[146:149], v199 offset:32768
	ds_read_b128 v[150:153], v199 offset:33792
	ds_read_b128 v[154:157], v199 offset:34816
	ds_read_b128 v[158:161], v199 offset:35840
	ds_read_b128 v[162:165], v199 offset:36864
	ds_read_b128 v[166:169], v199 offset:37888
	ds_read_b128 v[170:173], v199 offset:38912
	ds_read_b128 v[174:177], v199 offset:39936
	global_load_lds_dwordx4 v180, s[80:81]
	v_add_u32_e32 v180, s5, v185
	v_readfirstlane_b32 s5, v192
	s_mov_b32 m0, s5
	s_nop 0
	global_load_lds_dwordx4 v180, s[80:81]
	v_or_b32_e32 v180, 0x1c000, v200
	v_add_u32_e32 v202, 0x1c400, v200
	v_add_u32_e32 v206, 0x1c800, v200
	v_add_u32_e32 v210, 0x1cc00, v200
	ds_read_b128 v[180:183], v180
	ds_read_b128 v[202:205], v202
	ds_read_b128 v[206:209], v206
	ds_read_b128 v[210:213], v210
	s_waitcnt vmcnt(8)
	s_waitcnt lgkmcnt(0)
	s_barrier
	s_setprio 1
	v_mfma_f32_16x16x32_bf16 v[130:133], v[122:125], v[146:149], v[130:133]
	v_mfma_f32_16x16x32_bf16 v[126:129], v[138:141], v[146:149], v[126:129]
	v_mfma_f32_16x16x32_bf16 v[110:113], v[122:125], v[154:157], v[110:113]
	v_mfma_f32_16x16x32_bf16 v[106:109], v[138:141], v[154:157], v[106:109]
	v_mfma_f32_16x16x32_bf16 v[94:97], v[122:125], v[162:165], v[94:97]
	v_mfma_f32_16x16x32_bf16 v[90:93], v[138:141], v[162:165], v[90:93]
	v_mfma_f32_16x16x32_bf16 v[78:81], v[122:125], v[170:173], v[78:81]
	v_mfma_f32_16x16x32_bf16 v[74:77], v[138:141], v[170:173], v[74:77]
	v_mfma_f32_16x16x32_bf16 v[130:133], v[134:137], v[150:153], v[130:133]
	v_mfma_f32_16x16x32_bf16 v[126:129], v[142:145], v[150:153], v[126:129]
	v_mfma_f32_16x16x32_bf16 v[110:113], v[134:137], v[158:161], v[110:113]
	v_mfma_f32_16x16x32_bf16 v[106:109], v[142:145], v[158:161], v[106:109]
	v_mfma_f32_16x16x32_bf16 v[94:97], v[134:137], v[166:169], v[94:97]
	v_mfma_f32_16x16x32_bf16 v[90:93], v[142:145], v[166:169], v[90:93]
	v_mfma_f32_16x16x32_bf16 v[78:81], v[134:137], v[174:177], v[78:81]
	v_mfma_f32_16x16x32_bf16 v[74:77], v[142:145], v[174:177], v[74:77]
	v_mfma_f32_16x16x32_bf16 v[118:121], v[180:183], v[146:149], v[118:121]
	v_mfma_f32_16x16x32_bf16 v[114:117], v[206:209], v[146:149], v[114:117]
	v_mfma_f32_16x16x32_bf16 v[102:105], v[180:183], v[154:157], v[102:105]
	v_mfma_f32_16x16x32_bf16 v[98:101], v[206:209], v[154:157], v[98:101]
	v_mfma_f32_16x16x32_bf16 v[86:89], v[180:183], v[162:165], v[86:89]
	v_mfma_f32_16x16x32_bf16 v[82:85], v[206:209], v[162:165], v[82:85]
	v_mfma_f32_16x16x32_bf16 v[70:73], v[180:183], v[170:173], v[70:73]
	v_mfma_f32_16x16x32_bf16 v[66:69], v[206:209], v[170:173], v[66:69]
	v_mfma_f32_16x16x32_bf16 v[118:121], v[202:205], v[150:153], v[118:121]
	v_mfma_f32_16x16x32_bf16 v[114:117], v[210:213], v[150:153], v[114:117]
	v_mfma_f32_16x16x32_bf16 v[102:105], v[202:205], v[158:161], v[102:105]
	v_mfma_f32_16x16x32_bf16 v[98:101], v[210:213], v[158:161], v[98:101]
	v_mfma_f32_16x16x32_bf16 v[86:89], v[202:205], v[166:169], v[86:89]
	v_mfma_f32_16x16x32_bf16 v[82:85], v[210:213], v[166:169], v[82:85]
	v_mfma_f32_16x16x32_bf16 v[70:73], v[202:205], v[174:177], v[70:73]
	v_mfma_f32_16x16x32_bf16 v[66:69], v[210:213], v[174:177], v[66:69]
	s_setprio 0
	s_barrier
	s_or_b32 s5, s7, 64
	s_or_b32 s3, s5, s3
	s_lshl_b32 s3, s3, 1
	v_readfirstlane_b32 s6, v193
	v_add_u32_e32 v214, s3, v184
	s_mov_b32 m0, s6
	global_load_lds_dwordx4 v214, s[74:75]
	v_add_u32_e32 v214, s3, v185
	v_readfirstlane_b32 s3, v194
	s_mov_b32 m0, s3
	s_nop 0
	global_load_lds_dwordx4 v214, s[74:75]
	s_or_b32 s3, s5, s10
	s_lshl_b32 s3, s3, 1
	v_readfirstlane_b32 s6, v195
	v_add_u32_e32 v214, s3, v184
	s_mov_b32 m0, s6
	ds_read_b128 v[146:149], v199 offset:49152
	ds_read_b128 v[150:153], v199 offset:50176
	ds_read_b128 v[154:157], v199 offset:51200
	ds_read_b128 v[158:161], v199 offset:52224
	ds_read_b128 v[162:165], v199 offset:53248
	ds_read_b128 v[166:169], v199 offset:54272
	ds_read_b128 v[170:173], v199 offset:55296
	ds_read_b128 v[174:177], v199 offset:56320
	global_load_lds_dwordx4 v214, s[80:81]
	v_add_u32_e32 v214, s3, v185
	v_readfirstlane_b32 s3, v196
	s_mov_b32 m0, s3
	s_nop 0
	global_load_lds_dwordx4 v214, s[80:81]
	s_or_b32 s3, s11, s5
	s_lshl_b32 s3, s3, 1
	v_readfirstlane_b32 s5, v197
	v_add_u32_e32 v215, s3, v184
	s_mov_b32 m0, s5
	s_nop 0
	global_load_lds_dwordx4 v215, s[74:75]
	v_add_u32_e32 v215, s3, v185
	v_readfirstlane_b32 s3, v198
	s_mov_b32 m0, s3
	s_nop 0
	global_load_lds_dwordx4 v215, s[74:75]
	s_waitcnt vmcnt(8)
	s_waitcnt lgkmcnt(0)
	s_barrier
	s_setprio 1
	v_mfma_f32_16x16x32_bf16 v[62:65], v[122:125], v[146:149], v[62:65]
	v_mfma_f32_16x16x32_bf16 v[58:61], v[138:141], v[146:149], v[58:61]
	v_mfma_f32_16x16x32_bf16 v[46:49], v[122:125], v[154:157], v[46:49]
	v_mfma_f32_16x16x32_bf16 v[42:45], v[138:141], v[154:157], v[42:45]
	v_mfma_f32_16x16x32_bf16 v[30:33], v[122:125], v[162:165], v[30:33]
	v_mfma_f32_16x16x32_bf16 v[26:29], v[138:141], v[162:165], v[26:29]
	v_mfma_f32_16x16x32_bf16 v[14:17], v[122:125], v[170:173], v[14:17]
	v_mfma_f32_16x16x32_bf16 v[10:13], v[138:141], v[170:173], v[10:13]
	v_mfma_f32_16x16x32_bf16 v[62:65], v[134:137], v[150:153], v[62:65]
	v_mfma_f32_16x16x32_bf16 v[58:61], v[142:145], v[150:153], v[58:61]
	v_mfma_f32_16x16x32_bf16 v[46:49], v[134:137], v[158:161], v[46:49]
	v_mfma_f32_16x16x32_bf16 v[42:45], v[142:145], v[158:161], v[42:45]
	v_mfma_f32_16x16x32_bf16 v[30:33], v[134:137], v[166:169], v[30:33]
	v_mfma_f32_16x16x32_bf16 v[26:29], v[142:145], v[166:169], v[26:29]
	v_mfma_f32_16x16x32_bf16 v[14:17], v[134:137], v[174:177], v[14:17]
	v_mfma_f32_16x16x32_bf16 v[10:13], v[142:145], v[174:177], v[10:13]
	v_mfma_f32_16x16x32_bf16 v[54:57], v[180:183], v[146:149], v[54:57]
	v_mfma_f32_16x16x32_bf16 v[50:53], v[206:209], v[146:149], v[50:53]
	v_mfma_f32_16x16x32_bf16 v[38:41], v[180:183], v[154:157], v[38:41]
	v_mfma_f32_16x16x32_bf16 v[34:37], v[206:209], v[154:157], v[34:37]
	v_mfma_f32_16x16x32_bf16 v[22:25], v[180:183], v[162:165], v[22:25]
	v_mfma_f32_16x16x32_bf16 v[18:21], v[206:209], v[162:165], v[18:21]
	v_mfma_f32_16x16x32_bf16 v[6:9], v[180:183], v[170:173], v[6:9]
	v_mfma_f32_16x16x32_bf16 v[2:5], v[206:209], v[170:173], v[2:5]
	v_mfma_f32_16x16x32_bf16 v[54:57], v[202:205], v[150:153], v[54:57]
	v_mfma_f32_16x16x32_bf16 v[50:53], v[210:213], v[150:153], v[50:53]
	v_mfma_f32_16x16x32_bf16 v[38:41], v[202:205], v[158:161], v[38:41]
	v_mfma_f32_16x16x32_bf16 v[34:37], v[210:213], v[158:161], v[34:37]
	v_mfma_f32_16x16x32_bf16 v[22:25], v[202:205], v[166:169], v[22:25]
	v_mfma_f32_16x16x32_bf16 v[18:21], v[210:213], v[166:169], v[18:21]
	v_mfma_f32_16x16x32_bf16 v[6:9], v[202:205], v[174:177], v[6:9]
	v_mfma_f32_16x16x32_bf16 v[2:5], v[210:213], v[174:177], v[2:5]
	s_setprio 0
	s_add_i32 s0, s0, 2
	s_cmp_gt_u32 s1, 29
	v_add_u32_e32 v0, 0x100, v0
	s_barrier
	s_cbranch_scc0 .LBB0_414
